# weight conversion: 4-tile register ring really kept in flight now - tile data and row scales load straight into their ring slot with no wait in the loader; each store waits with a counted vmcnt for it
# speedup vs baseline: 1.0116x; 1.0047x over previous
.LBB0_211:
	s_add_i32 s34, s70, 63
	s_lshr_b32 s79, s34, 6
	s_add_i32 s34, s37, 63
	s_ashr_i32 s66, s34, 6
	s_mul_i32 s34, s11, 37
	s_add_i32 s34, s10, s34
	s_ashr_i32 s67, s34, 31
	s_abs_i32 s34, s34
	v_readlane_b32 s35, v251, 63
	s_mul_hi_u32 s35, s34, s35
	v_readlane_b32 s40, v251, 62
	s_mul_i32 s35, s35, s40
	s_sub_i32 s34, s34, s35
	s_sub_i32 s35, s34, s40
	s_cmp_ge_u32 s34, s40
	s_cselect_b32 s34, s35, s34
	s_sub_i32 s35, s34, s40
	s_cmp_ge_u32 s34, s40
	s_cselect_b32 s34, s35, s34
	s_xor_b32 s68, s34, s67
	s_sub_i32 s82, s68, s67
	s_mul_i32 s79, s79, s66
	s_cmp_lg_u64 s[6:7], 0
	s_cselect_b64 s[34:35], -1, 0
	s_cmp_lt_i32 s82, s79
	s_cselect_b64 s[40:41], -1, 0
	s_and_b64 vcc, exec, s[40:41]
	s_cbranch_vccz .LBB0_233
	s_abs_i32 s42, s66
	v_cvt_f32_u32_e32 v0, s42
	s_sub_i32 s45, 0, s42
	s_abs_i32 s44, s82
	s_xor_b32 s43, s82, s66
	v_rcp_iflag_f32_e32 v0, v0
	s_ashr_i32 s43, s43, 31
	v_mov_b32_e32 v2, v202
	v_mul_f32_e32 v0, 0x4f7ffffe, v0
	v_cvt_u32_f32_e32 v0, v0
	s_waitcnt lgkmcnt(0)
	v_ashrrev_i32_e32 v3, 4, v2
	v_mov_b32_e32 v46, 1.0
	v_readfirstlane_b32 s64, v0
	s_mul_i32 s45, s45, s64
	s_mul_hi_u32 s45, s64, s45
	s_add_i32 s64, s64, s45
	s_mul_hi_u32 s45, s44, s64
	s_mul_i32 s64, s45, s42
	s_sub_i32 s44, s44, s64
	s_add_i32 s65, s45, 1
	s_sub_i32 s64, s44, s42
	s_cmp_ge_u32 s44, s42
	s_cselect_b32 s45, s65, s45
	s_cselect_b32 s44, s64, s44
	s_add_i32 s64, s45, 1
	s_cmp_ge_u32 s44, s42
	s_cselect_b32 s42, s64, s45
	s_xor_b32 s42, s42, s43
	s_sub_i32 s43, s42, s43
	s_mul_i32 s42, s43, s66
	s_sub_i32 s42, s82, s42
	v_lshlrev_b32_e32 v0, 2, v2
	v_lshl_add_u32 v56, s43, 6, v3
	v_mov_b32_e32 v2, v1
	v_mov_b32_e32 v3, v1
	s_lshl_b32 s42, s42, 6
	v_and_b32_e32 v41, 60, v0
	v_mov_b32_e32 v0, v1
	v_mov_b64_e32 v[22:23], v[2:3]
	v_or_b32_e32 v43, s42, v41
	s_ashr_i32 s43, s42, 31
	v_cmp_gt_i32_e32 vcc, s70, v56
	v_mov_b64_e32 v[20:21], v[0:1]
	s_and_saveexec_b64 s[44:45], vcc
	s_cbranch_execz .LBB0_222
	v_mov_b32_e32 v2, v1
	v_mov_b32_e32 v3, v1
	v_mov_b32_e32 v0, v1
	v_mov_b64_e32 v[22:23], v[2:3]
	v_cmp_gt_i32_e32 vcc, s37, v43
	v_mov_b64_e32 v[20:21], v[0:1]
	s_and_saveexec_b64 s[64:65], vcc
	s_cbranch_execz .LBB0_215
	v_mad_i64_i32 v[2:3], s[84:85], v56, s37, 0
	v_lshl_add_u64 v[2:3], v[2:3], 2, s[0:1]
	v_lshl_add_u64 v[2:3], s[42:43], 2, v[2:3]
	v_lshlrev_b32_e32 v0, 2, v41
	v_lshl_add_u64 v[2:3], v[2:3], 0, v[0:1]
	global_load_dwordx4 v[20:23], v[2:3], off
	s_add_i32 s100, s101, 1
	s_min_u32 s100, s100, 3
	s_mov_b32 s101, 0
	s_cmp_lt_i32 s70, 64
	s_cbranch_scc1 .Lc3_skip0
	s_and_b32 s98, s37, 63
	s_cmp_lg_u32 s98, 0
	s_cbranch_scc1 .Lc3_skip0
	s_lshl_b32 s98, s37, 7
	v_add_co_u32_e32 v70, vcc, s98, v2
	s_nop 1
	v_addc_co_u32_e32 v71, vcc, 0, v3, vcc
	s_cmp_lg_u32 s39, 0
	s_cbranch_scc1 .Lc3_pf0
	v_mov_b32_e32 v46, 1.0
	v_mov_b32_e32 v54, 1.0
	global_load_dwordx4 v[36:39], v[70:71], off
	s_cmp_lg_u64 s[34:35], 0
	s_cbranch_scc0 .Lc3_ns0
	v_mov_b32_e32 v67, 0
	v_mov_b32_e32 v66, v56
	v_lshl_add_u64 v[68:69], v[66:67], 2, s[6:7]
	global_load_dword v46, v[68:69], off
	global_load_dword v54, v[68:69], off offset:128
	s_branch .Lc3_fin0
.Lc3_ns0:
	global_load_dword v66, v[2:3], off
	global_load_dword v67, v[2:3], off
.Lc3_fin0:
	s_mov_b32 s101, s100
	s_or_b64 exec, exec, s[64:65]
	s_or_b64 exec, exec, s[44:45]
	s_branch .Lc3_end0

.Lc3_end0:
.LBB0_233:
	v_readlane_b32 s42, v251, 60
	s_add_i32 s69, s82, s42
	s_add_i32 s100, s101, 1
	s_min_u32 s100, s100, 3
	s_mov_b32 s101, 0
	s_cmp_ge_i32 s69, s79
	s_cbranch_scc1 .LBB0_255
	s_abs_i32 s42, s66
	s_waitcnt vmcnt(0)
	v_cvt_f32_u32_e32 v0, s42
	s_sub_i32 s45, 0, s42
	s_abs_i32 s44, s69
	s_xor_b32 s43, s69, s66
	v_rcp_iflag_f32_e32 v0, v0
	s_ashr_i32 s43, s43, 31
	v_mov_b32_e32 v2, v202
	v_mul_f32_e32 v0, 0x4f7ffffe, v0
	v_cvt_u32_f32_e32 v0, v0
	s_waitcnt lgkmcnt(0)
	v_ashrrev_i32_e32 v3, 4, v2
	v_mov_b32_e32 v44, 1.0
	v_readfirstlane_b32 s64, v0
	s_mul_i32 s45, s45, s64
	s_mul_hi_u32 s45, s64, s45
	s_add_i32 s64, s64, s45
	s_mul_hi_u32 s45, s44, s64
	s_mul_i32 s64, s45, s42
	s_sub_i32 s44, s44, s64
	s_add_i32 s65, s45, 1
	s_sub_i32 s64, s44, s42
	s_cmp_ge_u32 s44, s42
	s_cselect_b32 s45, s65, s45
	s_cselect_b32 s44, s64, s44
	s_add_i32 s64, s45, 1
	s_cmp_ge_u32 s44, s42
	s_cselect_b32 s42, s64, s45
	s_xor_b32 s42, s42, s43
	s_sub_i32 s43, s42, s43
	s_mul_i32 s42, s43, s66
	s_sub_i32 s42, s69, s42
	v_lshlrev_b32_e32 v0, 2, v2
	v_lshl_add_u32 v56, s43, 6, v3
	v_mov_b32_e32 v2, v1
	v_mov_b32_e32 v3, v1
	s_lshl_b32 s42, s42, 6
	v_and_b32_e32 v41, 60, v0
	v_mov_b32_e32 v0, v1
	v_mov_b64_e32 v[18:19], v[2:3]
	v_or_b32_e32 v43, s42, v41
	s_ashr_i32 s43, s42, 31
	v_cmp_gt_i32_e32 vcc, s70, v56
	v_mov_b64_e32 v[16:17], v[0:1]
	s_and_saveexec_b64 s[44:45], vcc
	s_cbranch_execz .LBB0_244
	v_mov_b32_e32 v2, v1
	v_mov_b32_e32 v3, v1
	v_mov_b32_e32 v0, v1
	v_mov_b64_e32 v[18:19], v[2:3]
	v_cmp_gt_i32_e32 vcc, s37, v43
	v_mov_b64_e32 v[16:17], v[0:1]
	s_and_saveexec_b64 s[64:65], vcc
	s_cbranch_execz .LBB0_237
	v_mad_i64_i32 v[2:3], s[84:85], v56, s37, 0
	v_lshl_add_u64 v[2:3], v[2:3], 2, s[0:1]
	v_lshl_add_u64 v[2:3], s[42:43], 2, v[2:3]
	v_lshlrev_b32_e32 v0, 2, v41
	v_lshl_add_u64 v[2:3], v[2:3], 0, v[0:1]
	global_load_dwordx4 v[16:19], v[2:3], off
	s_cmp_lt_i32 s70, 64
	s_cbranch_scc1 .Lc3_skip1
	s_and_b32 s98, s37, 63
	s_cmp_lg_u32 s98, 0
	s_cbranch_scc1 .Lc3_skip1
	s_lshl_b32 s98, s37, 7
	v_add_co_u32_e32 v70, vcc, s98, v2
	s_nop 1
	v_addc_co_u32_e32 v71, vcc, 0, v3, vcc
	s_cmp_lg_u32 s39, 0
	s_cbranch_scc1 .Lc3_pf1
	v_mov_b32_e32 v44, 1.0
	v_mov_b32_e32 v50, 1.0
	global_load_dwordx4 v[32:35], v[70:71], off
	s_cmp_lg_u64 s[34:35], 0
	s_cbranch_scc0 .Lc3_ns1
	v_mov_b32_e32 v67, 0
	v_mov_b32_e32 v66, v56
	v_lshl_add_u64 v[68:69], v[66:67], 2, s[6:7]
	global_load_dword v44, v[68:69], off
	global_load_dword v50, v[68:69], off offset:128
	s_branch .Lc3_fin1

.Lc3_end1:
.LBB0_255:
	v_readlane_b32 s42, v251, 60
	s_add_i32 s69, s69, s42
	s_add_i32 s100, s101, 1
	s_min_u32 s100, s100, 3
	s_mov_b32 s101, 0
	s_cmp_ge_i32 s69, s79
	s_cbranch_scc1 .LBB0_277
	s_abs_i32 s42, s66
	s_waitcnt vmcnt(0)
	v_cvt_f32_u32_e32 v0, s42
	s_sub_i32 s45, 0, s42
	s_abs_i32 s44, s69
	s_xor_b32 s43, s69, s66
	v_rcp_iflag_f32_e32 v0, v0
	s_ashr_i32 s43, s43, 31
	v_mov_b32_e32 v2, v202
	v_mul_f32_e32 v0, 0x4f7ffffe, v0
	v_cvt_u32_f32_e32 v0, v0
	s_waitcnt lgkmcnt(0)
	v_ashrrev_i32_e32 v3, 4, v2
	v_mov_b32_e32 v40, 1.0
	v_readfirstlane_b32 s64, v0
	s_mul_i32 s45, s45, s64
	s_mul_hi_u32 s45, s64, s45
	s_add_i32 s64, s64, s45
	s_mul_hi_u32 s45, s44, s64
	s_mul_i32 s64, s45, s42
	s_sub_i32 s44, s44, s64
	s_add_i32 s65, s45, 1
	s_sub_i32 s64, s44, s42
	s_cmp_ge_u32 s44, s42
	s_cselect_b32 s45, s65, s45
	s_cselect_b32 s44, s64, s44
	s_add_i32 s64, s45, 1
	s_cmp_ge_u32 s44, s42
	s_cselect_b32 s42, s64, s45
	s_xor_b32 s42, s42, s43
	s_sub_i32 s43, s42, s43
	s_mul_i32 s42, s43, s66
	s_sub_i32 s42, s69, s42
	v_lshlrev_b32_e32 v0, 2, v2
	v_lshl_add_u32 v56, s43, 6, v3
	v_mov_b32_e32 v2, v1
	v_mov_b32_e32 v3, v1
	s_lshl_b32 s42, s42, 6
	v_and_b32_e32 v41, 60, v0
	v_mov_b32_e32 v0, v1
	v_mov_b64_e32 v[14:15], v[2:3]
	v_or_b32_e32 v43, s42, v41
	s_ashr_i32 s43, s42, 31
	v_cmp_gt_i32_e32 vcc, s70, v56
	v_mov_b64_e32 v[12:13], v[0:1]
	s_and_saveexec_b64 s[44:45], vcc
	s_cbranch_execz .LBB0_266
	v_mov_b32_e32 v2, v1
	v_mov_b32_e32 v3, v1
	v_mov_b32_e32 v0, v1
	v_mov_b64_e32 v[14:15], v[2:3]
	v_cmp_gt_i32_e32 vcc, s37, v43
	v_mov_b64_e32 v[12:13], v[0:1]
	s_and_saveexec_b64 s[64:65], vcc
	s_cbranch_execz .LBB0_259
	v_mad_i64_i32 v[2:3], s[84:85], v56, s37, 0
	v_lshl_add_u64 v[2:3], v[2:3], 2, s[0:1]
	v_lshl_add_u64 v[2:3], s[42:43], 2, v[2:3]
	v_lshlrev_b32_e32 v0, 2, v41
	v_lshl_add_u64 v[2:3], v[2:3], 0, v[0:1]
	global_load_dwordx4 v[12:15], v[2:3], off
	s_cmp_lt_i32 s70, 64
	s_cbranch_scc1 .Lc3_skip2
	s_and_b32 s98, s37, 63
	s_cmp_lg_u32 s98, 0
	s_cbranch_scc1 .Lc3_skip2
	s_lshl_b32 s98, s37, 7
	v_add_co_u32_e32 v70, vcc, s98, v2
	s_nop 1
	v_addc_co_u32_e32 v71, vcc, 0, v3, vcc
	s_cmp_lg_u32 s39, 0
	s_cbranch_scc1 .Lc3_pf2
	v_mov_b32_e32 v40, 1.0
	v_mov_b32_e32 v48, 1.0
	global_load_dwordx4 v[28:31], v[70:71], off
	s_cmp_lg_u64 s[34:35], 0
	s_cbranch_scc0 .Lc3_ns2
	v_mov_b32_e32 v67, 0
	v_mov_b32_e32 v66, v56
	v_lshl_add_u64 v[68:69], v[66:67], 2, s[6:7]
	global_load_dword v40, v[68:69], off
	global_load_dword v48, v[68:69], off offset:128
	s_branch .Lc3_fin2

.Lc3_end2:
.LBB0_277:
	v_readlane_b32 s42, v251, 60
	s_add_i32 s69, s69, s42
	s_add_i32 s100, s101, 1
	s_min_u32 s100, s100, 3
	s_mov_b32 s101, 0
	s_cmp_ge_i32 s69, s79
	s_cbranch_scc1 .LBB0_299
	s_abs_i32 s42, s66
	s_waitcnt vmcnt(0)
	v_cvt_f32_u32_e32 v0, s42
	s_sub_i32 s45, 0, s42
	s_abs_i32 s44, s69
	s_xor_b32 s43, s69, s66
	v_rcp_iflag_f32_e32 v0, v0
	s_ashr_i32 s43, s43, 31
	v_mov_b32_e32 v2, v202
	v_mul_f32_e32 v0, 0x4f7ffffe, v0
	v_cvt_u32_f32_e32 v0, v0
	s_waitcnt lgkmcnt(0)
	v_ashrrev_i32_e32 v3, 4, v2
	v_mov_b32_e32 v42, 1.0
	v_readfirstlane_b32 s64, v0
	s_mul_i32 s45, s45, s64
	s_mul_hi_u32 s45, s64, s45
	s_add_i32 s64, s64, s45
	s_mul_hi_u32 s45, s44, s64
	s_mul_i32 s64, s45, s42
	s_sub_i32 s44, s44, s64
	s_add_i32 s65, s45, 1
	s_sub_i32 s64, s44, s42
	s_cmp_ge_u32 s44, s42
	s_cselect_b32 s45, s65, s45
	s_cselect_b32 s44, s64, s44
	s_add_i32 s64, s45, 1
	s_cmp_ge_u32 s44, s42
	s_cselect_b32 s42, s64, s45
	s_xor_b32 s42, s42, s43
	s_sub_i32 s43, s42, s43
	s_mul_i32 s42, s43, s66
	s_sub_i32 s42, s69, s42
	v_lshlrev_b32_e32 v0, 2, v2
	v_lshl_add_u32 v56, s43, 6, v3
	v_mov_b32_e32 v2, v1
	v_mov_b32_e32 v3, v1
	s_lshl_b32 s42, s42, 6
	v_and_b32_e32 v41, 60, v0
	v_mov_b32_e32 v0, v1
	v_mov_b64_e32 v[10:11], v[2:3]
	v_or_b32_e32 v43, s42, v41
	s_ashr_i32 s43, s42, 31
	v_cmp_gt_i32_e32 vcc, s70, v56
	v_mov_b64_e32 v[8:9], v[0:1]
	s_and_saveexec_b64 s[44:45], vcc
	s_cbranch_execz .LBB0_288
	v_mov_b32_e32 v2, v1
	v_mov_b32_e32 v3, v1
	v_mov_b32_e32 v0, v1
	v_mov_b64_e32 v[10:11], v[2:3]
	v_cmp_gt_i32_e32 vcc, s37, v43
	v_mov_b64_e32 v[8:9], v[0:1]
	s_and_saveexec_b64 s[64:65], vcc
	s_cbranch_execz .LBB0_281
	v_mad_i64_i32 v[2:3], s[84:85], v56, s37, 0
	v_lshl_add_u64 v[2:3], v[2:3], 2, s[0:1]
	v_lshl_add_u64 v[2:3], s[42:43], 2, v[2:3]
	v_lshlrev_b32_e32 v0, 2, v41
	v_lshl_add_u64 v[2:3], v[2:3], 0, v[0:1]
	global_load_dwordx4 v[8:11], v[2:3], off
	s_cmp_lt_i32 s70, 64
	s_cbranch_scc1 .Lc3_skip3
	s_and_b32 s98, s37, 63
	s_cmp_lg_u32 s98, 0
	s_cbranch_scc1 .Lc3_skip3
	s_lshl_b32 s98, s37, 7
	v_add_co_u32_e32 v70, vcc, s98, v2
	s_nop 1
	v_addc_co_u32_e32 v71, vcc, 0, v3, vcc
	s_cmp_lg_u32 s39, 0
	s_cbranch_scc1 .Lc3_pf3
	v_mov_b32_e32 v42, 1.0
	v_mov_b32_e32 v52, 1.0
	global_load_dwordx4 v[24:27], v[70:71], off
	s_cmp_lg_u64 s[34:35], 0
	s_cbranch_scc0 .Lc3_ns3
	v_mov_b32_e32 v67, 0
	v_mov_b32_e32 v66, v56
	v_lshl_add_u64 v[68:69], v[66:67], 2, s[6:7]
	global_load_dword v42, v[68:69], off
	global_load_dword v52, v[68:69], off offset:128
	s_branch .Lc3_fin3

.LBB0_301:
	s_abs_i32 s41, s82
	s_mul_hi_u32 s42, s41, s87
	s_mul_i32 s43, s42, s83
	s_ashr_i32 s40, s82, 31
	s_sub_i32 s41, s41, s43
	s_xor_b32 s40, s40, s84
	s_add_i32 s43, s42, 1
	s_sub_i32 s44, s41, s83
	s_cmp_eq_u32 s101, 0
	s_cbranch_scc1 .Lc3_w0_0
	s_cmp_eq_u32 s101, 1
	s_cbranch_scc1 .Lc3_w4_0
	s_cmp_eq_u32 s101, 2
	s_cbranch_scc1 .Lc3_w8_0
	s_waitcnt vmcnt(12)
	s_branch .Lc3_wd_0
.Lc3_w8_0:
	s_waitcnt vmcnt(8)
	s_branch .Lc3_wd_0
.Lc3_w4_0:
	s_waitcnt vmcnt(4)
	s_branch .Lc3_wd_0

.Lc3_wd_0:
	v_mov_b32_e32 v0, v202
	s_cmp_ge_u32 s41, s83
	s_cselect_b32 s42, s43, s42
	v_ashrrev_i32_e32 v2, 4, v0
	s_waitcnt lgkmcnt(0)
	v_lshlrev_b32_e32 v3, 4, v0
	s_cselect_b32 s41, s44, s41
	s_add_i32 s43, s42, 1
	v_and_b32_e32 v3, 0xf0, v3
	v_mul_lo_u32 v2, v2, s3
	s_cmp_ge_u32 s41, s83
	v_add3_u32 v41, 0, v3, v2
	v_pk_mul_f32 v[2:3], v[46:47], v[20:21] op_sel_hi:[0,1]
	s_cselect_b32 s41, s43, s42
	ds_write2_b32 v41, v2, v3 offset1:1
	v_pk_mul_f32 v[2:3], v[46:47], v[22:23] op_sel_hi:[0,1]
	s_xor_b32 s41, s41, s40
	ds_write2_b32 v41, v2, v3 offset0:2 offset1:3
	v_add_u32_e32 v43, 0x2080, v41
	v_pk_mul_f32 v[2:3], v[54:55], v[36:37] op_sel_hi:[0,1]
	s_sub_i32 s42, s41, s40
	ds_write2_b32 v43, v2, v3 offset1:1
	v_add_u32_e32 v41, 0x2088, v41
	v_pk_mul_f32 v[2:3], v[54:55], v[38:39] op_sel_hi:[0,1]
	ds_write2_b32 v41, v2, v3 offset1:1
	v_ashrrev_i32_e32 v2, 3, v0
	s_mul_i32 s40, s85, s42
	s_waitcnt lgkmcnt(0)
	s_barrier
	v_subrev_u32_e32 v3, s40, v2
	v_add_u32_e32 v41, s86, v3
	v_cmp_gt_i32_e32 vcc, s37, v41
	s_and_saveexec_b64 s[40:41], vcc
	s_cbranch_execz .LBB0_314
	v_lshlrev_b32_e32 v0, 3, v0
	s_lshl_b32 s42, s42, 6
	v_and_b32_e32 v0, 56, v0
	v_or_b32_e32 v3, s42, v0
	v_cmp_gt_i32_e32 vcc, s71, v3
	s_and_b64 exec, exec, vcc
	s_cbranch_execz .LBB0_314
	v_lshlrev_b32_e32 v45, 2, v2
	v_mul_u32_u24_e32 v2, 0x104, v0
	v_add3_u32 v43, 0, v45, v2
	ds_read2_b32 v[2:3], v43 offset1:65
	ds_read2_b32 v[56:57], v43 offset0:130 offset1:195
	v_add_u32_e32 v43, 0x400, v43
	ds_read2_b32 v[58:59], v43 offset0:4 offset1:69
	ds_read2_b32 v[60:61], v43 offset0:134 offset1:199
	s_mov_b64 s[66:67], -1
	s_mov_b64 s[44:45], 0
	s_cmp_lt_i32 s38, 2
	s_mov_b64 s[64:65], 0
	s_cbranch_scc1 .LBB0_309
	s_cmp_eq_u32 s38, 2
	s_mov_b64 s[64:65], -1
	s_cbranch_scc0 .LBB0_306
	v_and_b32_e32 v43, 0x80, v45
	v_lshrrev_b32_e32 v45, 1, v41
	v_and_b32_e32 v45, 0x60, v45
	v_and_b32_e32 v47, 0xffffff1f, v41
	v_or3_b32 v43, v47, v43, v45
	s_mov_b64 s[64:65], 0

.LBB0_314:
	s_or_b64 exec, exec, s[40:41]
	v_readlane_b32 s40, v251, 55
	s_add_i32 s89, s82, s40
	s_waitcnt lgkmcnt(0)
	s_barrier
	s_add_i32 s100, s101, 1
	s_min_u32 s100, s100, 3
	s_mov_b32 s101, 0
	s_cmp_ge_i32 s89, s79
	s_cselect_b64 s[40:41], -1, 0
	s_and_b64 vcc, exec, s[40:41]
	s_cbranch_vccnz .LBB0_342
	s_abs_i32 s43, s89
	s_mul_hi_u32 s44, s43, s87
	s_mul_i32 s45, s44, s83
	s_ashr_i32 s42, s89, 31
	s_sub_i32 s43, s43, s45
	s_xor_b32 s42, s42, s84
	s_add_i32 s45, s44, 1
	s_sub_i32 s64, s43, s83
	s_cmp_ge_u32 s43, s83
	s_cselect_b32 s44, s45, s44
	s_cselect_b32 s43, s64, s43
	s_add_i32 s45, s44, 1
	s_cmp_ge_u32 s43, s83
	v_mov_b32_e32 v0, v202
	s_cselect_b32 s43, s45, s44
	s_xor_b32 s43, s43, s42
	s_sub_i32 s43, s43, s42
	v_ashrrev_i32_e32 v2, 4, v0
	v_lshlrev_b32_e32 v0, 2, v0
	s_mul_i32 s42, s88, s43
	v_readlane_b32 s44, v252, 10
	v_and_b32_e32 v41, 60, v0
	v_lshl_add_u32 v56, s43, 6, v2
	s_mul_i32 s43, s85, s43
	s_add_i32 s44, s44, s86
	v_subrev_u32_e32 v0, s43, v41
	v_mov_b32_e32 v2, v1
	v_mov_b32_e32 v3, v1
	s_add_i32 s42, s44, s42
	v_add_u32_e32 v43, s44, v0
	v_mov_b32_e32 v0, v1
	v_mov_b64_e32 v[22:23], v[2:3]
	s_ashr_i32 s43, s42, 31
	v_cmp_gt_i32_e32 vcc, s70, v56
	v_mov_b32_e32 v46, 1.0
	v_mov_b64_e32 v[20:21], v[0:1]
	s_and_saveexec_b64 s[44:45], vcc
	s_cbranch_execz .LBB0_328
	v_mov_b32_e32 v2, v1
	v_mov_b32_e32 v3, v1
	v_mov_b32_e32 v0, v1
	v_mov_b64_e32 v[22:23], v[2:3]
	v_cmp_gt_i32_e32 vcc, s37, v43
	v_mov_b64_e32 v[20:21], v[0:1]
	s_and_saveexec_b64 s[64:65], vcc
	s_cbranch_execz .LBB0_318
	v_mad_i64_i32 v[2:3], s[66:67], v56, s37, 0
	v_lshl_add_u64 v[2:3], v[2:3], 2, s[0:1]
	v_lshl_add_u64 v[2:3], s[42:43], 2, v[2:3]
	v_lshlrev_b32_e32 v0, 2, v41
	v_lshl_add_u64 v[2:3], v[2:3], 0, v[0:1]
	global_load_dwordx4 v[20:23], v[2:3], off
	s_cmp_lt_i32 s70, 64
	s_cbranch_scc1 .Lc3_skip4
	s_and_b32 s98, s37, 63
	s_cmp_lg_u32 s98, 0
	s_cbranch_scc1 .Lc3_skip4
	s_lshl_b32 s98, s37, 7
	v_add_co_u32_e32 v70, vcc, s98, v2
	s_nop 1
	v_addc_co_u32_e32 v71, vcc, 0, v3, vcc
	s_cmp_lg_u32 s39, 0
	s_cbranch_scc1 .Lc3_pf4
	v_mov_b32_e32 v46, 1.0
	v_mov_b32_e32 v54, 1.0
	global_load_dwordx4 v[36:39], v[70:71], off
	s_cmp_lg_u64 s[34:35], 0
	s_cbranch_scc0 .Lc3_ns4
	v_mov_b32_e32 v67, 0
	v_mov_b32_e32 v66, v56
	v_lshl_add_u64 v[68:69], v[66:67], 2, s[6:7]
	global_load_dword v46, v[68:69], off
	global_load_dword v54, v[68:69], off offset:128
	s_branch .Lc3_fin4

.Lc3_end4:
.LBB0_342:
	v_readlane_b32 s42, v251, 60
	s_add_i32 s42, s42, s82
	s_cmp_ge_i32 s42, s79
	s_cbranch_scc1 .LBB0_384
	s_ashr_i32 s43, s42, 31
	s_abs_i32 s42, s42
	s_mul_hi_u32 s44, s42, s87
	s_mul_i32 s45, s44, s83
	s_sub_i32 s42, s42, s45
	s_xor_b32 s43, s43, s84
	s_add_i32 s45, s44, 1
	s_sub_i32 s64, s42, s83
	s_cmp_eq_u32 s101, 0
	s_cbranch_scc1 .Lc3_w0_1
	s_cmp_eq_u32 s101, 1
	s_cbranch_scc1 .Lc3_w4_1
	s_cmp_eq_u32 s101, 2
	s_cbranch_scc1 .Lc3_w8_1
	s_waitcnt vmcnt(12)
	s_branch .Lc3_wd_1

.Lc3_wd_1:
	v_mov_b32_e32 v0, v202
	s_cmp_ge_u32 s42, s83
	s_cselect_b32 s44, s45, s44
	v_ashrrev_i32_e32 v2, 4, v0
	v_lshlrev_b32_e32 v3, 4, v0
	s_cselect_b32 s42, s64, s42
	s_add_i32 s45, s44, 1
	v_and_b32_e32 v3, 0xf0, v3
	v_mul_lo_u32 v2, v2, s3
	s_cmp_ge_u32 s42, s83
	v_add3_u32 v41, 0, v3, v2
	v_pk_mul_f32 v[2:3], v[44:45], v[16:17] op_sel_hi:[0,1]
	s_cselect_b32 s42, s45, s44
	ds_write2_b32 v41, v2, v3 offset1:1
	v_pk_mul_f32 v[2:3], v[44:45], v[18:19] op_sel_hi:[0,1]
	s_xor_b32 s42, s42, s43
	ds_write2_b32 v41, v2, v3 offset0:2 offset1:3
	v_add_u32_e32 v43, 0x2080, v41
	v_pk_mul_f32 v[2:3], v[50:51], v[32:33] op_sel_hi:[0,1]
	s_sub_i32 s44, s42, s43
	ds_write2_b32 v43, v2, v3 offset1:1
	v_add_u32_e32 v41, 0x2088, v41
	v_pk_mul_f32 v[2:3], v[50:51], v[34:35] op_sel_hi:[0,1]
	ds_write2_b32 v41, v2, v3 offset1:1
	v_ashrrev_i32_e32 v2, 3, v0
	s_mul_i32 s42, s85, s44
	v_subrev_u32_e32 v3, s42, v2
	v_readlane_b32 s42, v252, 16
	s_waitcnt lgkmcnt(0)
	s_barrier
	s_add_i32 s42, s42, s86
	v_add_u32_e32 v41, s42, v3
	v_cmp_gt_i32_e32 vcc, s37, v41
	s_and_saveexec_b64 s[42:43], vcc
	s_cbranch_execz .LBB0_356
	v_lshlrev_b32_e32 v0, 3, v0
	s_lshl_b32 s44, s44, 6
	v_and_b32_e32 v0, 56, v0
	v_or_b32_e32 v3, s44, v0
	v_cmp_gt_i32_e32 vcc, s71, v3
	s_and_b64 exec, exec, vcc
	s_cbranch_execz .LBB0_356
	v_lshlrev_b32_e32 v45, 2, v2
	v_mul_u32_u24_e32 v2, 0x104, v0
	v_add3_u32 v43, 0, v45, v2
	ds_read2_b32 v[2:3], v43 offset1:65
	ds_read2_b32 v[56:57], v43 offset0:130 offset1:195
	v_add_u32_e32 v43, 0x400, v43
	ds_read2_b32 v[58:59], v43 offset0:4 offset1:69
	ds_read2_b32 v[60:61], v43 offset0:134 offset1:199
	s_mov_b64 s[68:69], -1
	s_mov_b64 s[64:65], 0
	s_cmp_lt_i32 s38, 2
	s_mov_b64 s[66:67], 0
	s_cbranch_scc1 .LBB0_351
	s_cmp_eq_u32 s38, 2
	s_mov_b64 s[66:67], -1
	s_cbranch_scc0 .LBB0_348
	v_and_b32_e32 v43, 0x80, v45
	v_lshrrev_b32_e32 v45, 1, v41
	v_and_b32_e32 v45, 0x60, v45
	v_and_b32_e32 v47, 0xffffff1f, v41
	v_or3_b32 v43, v47, v43, v45
	s_mov_b64 s[66:67], 0

.LBB0_356:
	s_or_b64 exec, exec, s[42:43]
	s_waitcnt lgkmcnt(0)
	s_barrier
	v_readlane_b32 s42, v252, 17
	s_add_i32 s42, s42, s82
	s_add_i32 s100, s101, 1
	s_min_u32 s100, s100, 3
	s_mov_b32 s101, 0
	s_cmp_ge_i32 s42, s79
	s_cbranch_scc1 .LBB0_384
	s_ashr_i32 s43, s42, 31
	s_abs_i32 s42, s42
	s_mul_hi_u32 s44, s42, s87
	s_mul_i32 s45, s44, s83
	s_sub_i32 s42, s42, s45
	s_xor_b32 s43, s43, s84
	s_add_i32 s45, s44, 1
	s_sub_i32 s64, s42, s83
	s_cmp_ge_u32 s42, s83
	s_cselect_b32 s44, s45, s44
	s_cselect_b32 s42, s64, s42
	s_add_i32 s45, s44, 1
	s_cmp_ge_u32 s42, s83
	v_mov_b32_e32 v0, v202
	s_cselect_b32 s42, s45, s44
	s_xor_b32 s42, s42, s43
	s_sub_i32 s43, s42, s43
	v_ashrrev_i32_e32 v2, 4, v0
	v_lshlrev_b32_e32 v0, 2, v0
	s_mul_i32 s42, s88, s43
	v_readlane_b32 s44, v252, 18
	v_and_b32_e32 v41, 60, v0
	v_lshl_add_u32 v56, s43, 6, v2
	s_mul_i32 s43, s85, s43
	s_add_i32 s44, s44, s86
	v_subrev_u32_e32 v0, s43, v41
	v_mov_b32_e32 v2, v1
	v_mov_b32_e32 v3, v1
	s_add_i32 s42, s44, s42
	v_add_u32_e32 v43, s44, v0
	v_mov_b32_e32 v0, v1
	v_mov_b64_e32 v[18:19], v[2:3]
	s_ashr_i32 s43, s42, 31
	v_cmp_gt_i32_e32 vcc, s70, v56
	v_mov_b32_e32 v44, 1.0
	v_mov_b64_e32 v[16:17], v[0:1]
	s_and_saveexec_b64 s[44:45], vcc
	s_cbranch_execz .LBB0_370
	v_mov_b32_e32 v2, v1
	v_mov_b32_e32 v3, v1
	v_mov_b32_e32 v0, v1
	v_mov_b64_e32 v[18:19], v[2:3]
	v_cmp_gt_i32_e32 vcc, s37, v43
	v_mov_b64_e32 v[16:17], v[0:1]
	s_and_saveexec_b64 s[64:65], vcc
	s_cbranch_execz .LBB0_360
	v_mad_i64_i32 v[2:3], s[66:67], v56, s37, 0
	v_lshl_add_u64 v[2:3], v[2:3], 2, s[0:1]
	v_lshl_add_u64 v[2:3], s[42:43], 2, v[2:3]
	v_lshlrev_b32_e32 v0, 2, v41
	v_lshl_add_u64 v[2:3], v[2:3], 0, v[0:1]
	global_load_dwordx4 v[16:19], v[2:3], off
	s_cmp_lt_i32 s70, 64
	s_cbranch_scc1 .Lc3_skip5
	s_and_b32 s98, s37, 63
	s_cmp_lg_u32 s98, 0
	s_cbranch_scc1 .Lc3_skip5
	s_lshl_b32 s98, s37, 7
	v_add_co_u32_e32 v70, vcc, s98, v2
	s_nop 1
	v_addc_co_u32_e32 v71, vcc, 0, v3, vcc
	s_cmp_lg_u32 s39, 0
	s_cbranch_scc1 .Lc3_pf5
	v_mov_b32_e32 v44, 1.0
	v_mov_b32_e32 v50, 1.0
	global_load_dwordx4 v[32:35], v[70:71], off
	s_cmp_lg_u64 s[34:35], 0
	s_cbranch_scc0 .Lc3_ns5
	v_mov_b32_e32 v67, 0
	v_mov_b32_e32 v66, v56
	v_lshl_add_u64 v[68:69], v[66:67], 2, s[6:7]
	global_load_dword v44, v[68:69], off
	global_load_dword v50, v[68:69], off offset:128
	s_branch .Lc3_fin5

.Lc3_end5:
.LBB0_384:
	v_readlane_b32 s42, v251, 56
	s_add_i32 s42, s42, s82
	s_cmp_ge_i32 s42, s79
	s_cbranch_scc1 .LBB0_426
	s_ashr_i32 s43, s42, 31
	s_abs_i32 s42, s42
	s_mul_hi_u32 s44, s42, s87
	s_mul_i32 s45, s44, s83
	s_sub_i32 s42, s42, s45
	s_cmp_eq_u32 s101, 0
	s_cbranch_scc1 .Lc3_w0_2
	s_cmp_eq_u32 s101, 1
	s_cbranch_scc1 .Lc3_w4_2
	s_cmp_eq_u32 s101, 2
	s_cbranch_scc1 .Lc3_w8_2
	s_waitcnt vmcnt(12)
	s_branch .Lc3_wd_2

.Lc3_wd_2:
	v_mov_b32_e32 v0, v202
	s_xor_b32 s43, s43, s84
	s_add_i32 s45, s44, 1
	s_sub_i32 s64, s42, s83
	s_cmp_ge_u32 s42, s83
	v_ashrrev_i32_e32 v2, 4, v0
	v_lshlrev_b32_e32 v3, 4, v0
	s_cselect_b32 s44, s45, s44
	v_and_b32_e32 v3, 0xf0, v3
	v_mul_lo_u32 v2, v2, s3
	s_cselect_b32 s42, s64, s42
	s_add_i32 s45, s44, 1
	v_add3_u32 v41, 0, v3, v2
	s_cmp_ge_u32 s42, s83
	v_pk_mul_f32 v[2:3], v[40:41], v[12:13] op_sel_hi:[0,1]
	s_cselect_b32 s42, s45, s44
	ds_write2_b32 v41, v2, v3 offset1:1
	v_pk_mul_f32 v[2:3], v[40:41], v[14:15] op_sel_hi:[0,1]
	s_xor_b32 s42, s42, s43
	ds_write2_b32 v41, v2, v3 offset0:2 offset1:3
	v_add_u32_e32 v43, 0x2080, v41
	v_pk_mul_f32 v[2:3], v[48:49], v[28:29] op_sel_hi:[0,1]
	s_sub_i32 s44, s42, s43
	ds_write2_b32 v43, v2, v3 offset1:1
	v_add_u32_e32 v41, 0x2088, v41
	v_pk_mul_f32 v[2:3], v[48:49], v[30:31] op_sel_hi:[0,1]
	ds_write2_b32 v41, v2, v3 offset1:1
	v_ashrrev_i32_e32 v2, 3, v0
	s_mul_i32 s42, s85, s44
	v_subrev_u32_e32 v3, s42, v2
	v_readlane_b32 s42, v252, 13
	s_waitcnt lgkmcnt(0)
	s_barrier
	s_add_i32 s42, s42, s86
	v_add_u32_e32 v41, s42, v3
	v_cmp_gt_i32_e32 vcc, s37, v41
	s_and_saveexec_b64 s[42:43], vcc
	s_cbranch_execz .LBB0_398
	v_lshlrev_b32_e32 v0, 3, v0
	s_lshl_b32 s44, s44, 6
	v_and_b32_e32 v0, 56, v0
	v_or_b32_e32 v3, s44, v0
	v_cmp_gt_i32_e32 vcc, s71, v3
	s_and_b64 exec, exec, vcc
	s_cbranch_execz .LBB0_398
	v_lshlrev_b32_e32 v45, 2, v2
	v_mul_u32_u24_e32 v2, 0x104, v0
	v_add3_u32 v43, 0, v45, v2
	ds_read2_b32 v[2:3], v43 offset1:65
	ds_read2_b32 v[56:57], v43 offset0:130 offset1:195
	v_add_u32_e32 v43, 0x400, v43
	ds_read2_b32 v[58:59], v43 offset0:4 offset1:69
	ds_read2_b32 v[60:61], v43 offset0:134 offset1:199
	s_mov_b64 s[68:69], -1
	s_mov_b64 s[64:65], 0
	s_cmp_lt_i32 s38, 2
	s_mov_b64 s[66:67], 0
	s_cbranch_scc1 .LBB0_393
	s_cmp_eq_u32 s38, 2
	s_mov_b64 s[66:67], -1
	s_cbranch_scc0 .LBB0_390
	v_and_b32_e32 v43, 0x80, v45
	v_lshrrev_b32_e32 v45, 1, v41
	v_and_b32_e32 v45, 0x60, v45
	v_and_b32_e32 v47, 0xffffff1f, v41
	v_or3_b32 v43, v47, v43, v45
	s_mov_b64 s[66:67], 0

.LBB0_398:
	s_or_b64 exec, exec, s[42:43]
	s_waitcnt lgkmcnt(0)
	s_barrier
	v_readlane_b32 s42, v252, 14
	s_add_i32 s42, s42, s82
	s_add_i32 s100, s101, 1
	s_min_u32 s100, s100, 3
	s_mov_b32 s101, 0
	s_cmp_ge_i32 s42, s79
	s_cbranch_scc1 .LBB0_426
	s_ashr_i32 s43, s42, 31
	s_abs_i32 s42, s42
	s_mul_hi_u32 s44, s42, s87
	s_mul_i32 s45, s44, s83
	s_sub_i32 s42, s42, s45
	s_xor_b32 s43, s43, s84
	s_add_i32 s45, s44, 1
	s_sub_i32 s64, s42, s83
	s_cmp_ge_u32 s42, s83
	s_cselect_b32 s44, s45, s44
	s_cselect_b32 s42, s64, s42
	s_add_i32 s45, s44, 1
	s_cmp_ge_u32 s42, s83
	v_mov_b32_e32 v0, v202
	s_cselect_b32 s42, s45, s44
	s_xor_b32 s42, s42, s43
	s_sub_i32 s43, s42, s43
	v_ashrrev_i32_e32 v2, 4, v0
	v_lshlrev_b32_e32 v0, 2, v0
	s_mul_i32 s42, s88, s43
	v_readlane_b32 s44, v252, 15
	v_and_b32_e32 v41, 60, v0
	v_lshl_add_u32 v56, s43, 6, v2
	s_mul_i32 s43, s85, s43
	s_add_i32 s44, s44, s86
	v_subrev_u32_e32 v0, s43, v41
	v_mov_b32_e32 v2, v1
	v_mov_b32_e32 v3, v1
	s_add_i32 s42, s44, s42
	v_add_u32_e32 v43, s44, v0
	v_mov_b32_e32 v0, v1
	v_mov_b64_e32 v[14:15], v[2:3]
	s_ashr_i32 s43, s42, 31
	v_cmp_gt_i32_e32 vcc, s70, v56
	v_mov_b32_e32 v40, 1.0
	v_mov_b64_e32 v[12:13], v[0:1]
	s_and_saveexec_b64 s[44:45], vcc
	s_cbranch_execz .LBB0_412
	v_mov_b32_e32 v2, v1
	v_mov_b32_e32 v3, v1
	v_mov_b32_e32 v0, v1
	v_mov_b64_e32 v[14:15], v[2:3]
	v_cmp_gt_i32_e32 vcc, s37, v43
	v_mov_b64_e32 v[12:13], v[0:1]
	s_and_saveexec_b64 s[64:65], vcc
	s_cbranch_execz .LBB0_402
	v_mad_i64_i32 v[2:3], s[66:67], v56, s37, 0
	v_lshl_add_u64 v[2:3], v[2:3], 2, s[0:1]
	v_lshl_add_u64 v[2:3], s[42:43], 2, v[2:3]
	v_lshlrev_b32_e32 v0, 2, v41
	v_lshl_add_u64 v[2:3], v[2:3], 0, v[0:1]
	global_load_dwordx4 v[12:15], v[2:3], off
	s_cmp_lt_i32 s70, 64
	s_cbranch_scc1 .Lc3_skip6
	s_and_b32 s98, s37, 63
	s_cmp_lg_u32 s98, 0
	s_cbranch_scc1 .Lc3_skip6
	s_lshl_b32 s98, s37, 7
	v_add_co_u32_e32 v70, vcc, s98, v2
	s_nop 1
	v_addc_co_u32_e32 v71, vcc, 0, v3, vcc
	s_cmp_lg_u32 s39, 0
	s_cbranch_scc1 .Lc3_pf6
	v_mov_b32_e32 v40, 1.0
	v_mov_b32_e32 v48, 1.0
	global_load_dwordx4 v[28:31], v[70:71], off
	s_cmp_lg_u64 s[34:35], 0
	s_cbranch_scc0 .Lc3_ns6
	v_mov_b32_e32 v67, 0
	v_mov_b32_e32 v66, v56
	v_lshl_add_u64 v[68:69], v[66:67], 2, s[6:7]
	global_load_dword v40, v[68:69], off
	global_load_dword v48, v[68:69], off offset:128
	s_branch .Lc3_fin6

.Lc3_end6:
.LBB0_426:
	v_readlane_b32 s42, v251, 57
	s_add_i32 s42, s42, s82
	s_cmp_ge_i32 s42, s79
	s_cbranch_scc1 .LBB0_468
	s_ashr_i32 s43, s42, 31
	s_abs_i32 s42, s42
	s_mul_hi_u32 s44, s42, s87
	s_mul_i32 s45, s44, s83
	s_sub_i32 s42, s42, s45
	s_xor_b32 s43, s43, s84
	s_add_i32 s45, s44, 1
	s_sub_i32 s64, s42, s83
	s_cmp_eq_u32 s101, 0
	s_cbranch_scc1 .Lc3_w0_3
	s_cmp_eq_u32 s101, 1
	s_cbranch_scc1 .Lc3_w4_3
	s_cmp_eq_u32 s101, 2
	s_cbranch_scc1 .Lc3_w8_3
	s_waitcnt vmcnt(12)
	s_branch .Lc3_wd_3

.Lc3_wd_3:
	v_mov_b32_e32 v0, v202
	s_cmp_ge_u32 s42, s83
	s_cselect_b32 s44, s45, s44
	v_ashrrev_i32_e32 v2, 4, v0
	v_lshlrev_b32_e32 v3, 4, v0
	s_cselect_b32 s42, s64, s42
	s_add_i32 s45, s44, 1
	v_and_b32_e32 v3, 0xf0, v3
	v_mul_lo_u32 v2, v2, s3
	s_cmp_ge_u32 s42, s83
	v_add3_u32 v41, 0, v3, v2
	v_pk_mul_f32 v[2:3], v[8:9], v[42:43] op_sel_hi:[1,0]
	s_cselect_b32 s42, s45, s44
	ds_write2_b32 v41, v2, v3 offset1:1
	v_pk_mul_f32 v[2:3], v[10:11], v[42:43] op_sel_hi:[1,0]
	s_xor_b32 s42, s42, s43
	ds_write2_b32 v41, v2, v3 offset0:2 offset1:3
	v_add_u32_e32 v43, 0x2080, v41
	v_pk_mul_f32 v[2:3], v[24:25], v[52:53] op_sel_hi:[1,0]
	s_sub_i32 s44, s42, s43
	ds_write2_b32 v43, v2, v3 offset1:1
	v_add_u32_e32 v41, 0x2088, v41
	v_pk_mul_f32 v[2:3], v[26:27], v[52:53] op_sel_hi:[1,0]
	ds_write2_b32 v41, v2, v3 offset1:1
	v_ashrrev_i32_e32 v2, 3, v0
	s_mul_i32 s42, s85, s44
	v_subrev_u32_e32 v3, s42, v2
	v_readlane_b32 s42, v252, 9
	s_waitcnt lgkmcnt(0)
	s_barrier
	s_add_i32 s42, s42, s86
	v_add_u32_e32 v41, s42, v3
	v_cmp_gt_i32_e32 vcc, s37, v41
	s_and_saveexec_b64 s[42:43], vcc
	s_cbranch_execz .LBB0_440
	v_lshlrev_b32_e32 v0, 3, v0
	s_lshl_b32 s44, s44, 6
	v_and_b32_e32 v0, 56, v0
	v_or_b32_e32 v3, s44, v0
	v_cmp_gt_i32_e32 vcc, s71, v3
	s_and_b64 exec, exec, vcc
	s_cbranch_execz .LBB0_440
	v_lshlrev_b32_e32 v45, 2, v2
	v_mul_u32_u24_e32 v2, 0x104, v0
	v_add3_u32 v43, 0, v45, v2
	ds_read2_b32 v[2:3], v43 offset1:65
	ds_read2_b32 v[56:57], v43 offset0:130 offset1:195
	v_add_u32_e32 v43, 0x400, v43
	ds_read2_b32 v[58:59], v43 offset0:4 offset1:69
	ds_read2_b32 v[60:61], v43 offset0:134 offset1:199
	s_mov_b64 s[68:69], -1
	s_mov_b64 s[64:65], 0
	s_cmp_lt_i32 s38, 2
	s_mov_b64 s[66:67], 0
	s_cbranch_scc1 .LBB0_435
	s_cmp_eq_u32 s38, 2
	s_mov_b64 s[66:67], -1
	s_cbranch_scc0 .LBB0_432
	v_and_b32_e32 v43, 0x80, v45
	v_lshrrev_b32_e32 v45, 1, v41
	v_and_b32_e32 v45, 0x60, v45
	v_and_b32_e32 v47, 0xffffff1f, v41
	v_or3_b32 v43, v47, v43, v45
	s_mov_b64 s[66:67], 0

.LBB0_440:
	s_or_b64 exec, exec, s[42:43]
	s_waitcnt lgkmcnt(0)
	s_barrier
	v_readlane_b32 s42, v252, 11
	s_add_i32 s42, s42, s82
	s_add_i32 s100, s101, 1
	s_min_u32 s100, s100, 3
	s_mov_b32 s101, 0
	s_cmp_ge_i32 s42, s79
	s_cbranch_scc1 .LBB0_468
	s_ashr_i32 s43, s42, 31
	s_abs_i32 s42, s42
	s_mul_hi_u32 s44, s42, s87
	s_mul_i32 s45, s44, s83
	s_sub_i32 s42, s42, s45
	s_xor_b32 s43, s43, s84
	s_add_i32 s45, s44, 1
	s_sub_i32 s64, s42, s83
	s_cmp_ge_u32 s42, s83
	s_cselect_b32 s44, s45, s44
	s_cselect_b32 s42, s64, s42
	s_add_i32 s45, s44, 1
	s_cmp_ge_u32 s42, s83
	v_mov_b32_e32 v0, v202
	s_cselect_b32 s42, s45, s44
	s_xor_b32 s42, s42, s43
	s_sub_i32 s43, s42, s43
	v_ashrrev_i32_e32 v2, 4, v0
	v_lshlrev_b32_e32 v0, 2, v0
	s_mul_i32 s42, s88, s43
	v_readlane_b32 s44, v252, 12
	v_and_b32_e32 v41, 60, v0
	v_lshl_add_u32 v56, s43, 6, v2
	s_mul_i32 s43, s85, s43
	s_add_i32 s44, s44, s86
	v_subrev_u32_e32 v0, s43, v41
	v_mov_b32_e32 v2, v1
	v_mov_b32_e32 v3, v1
	s_add_i32 s42, s44, s42
	v_add_u32_e32 v43, s44, v0
	v_mov_b32_e32 v0, v1
	v_mov_b64_e32 v[10:11], v[2:3]
	s_ashr_i32 s43, s42, 31
	v_cmp_gt_i32_e32 vcc, s70, v56
	v_mov_b32_e32 v42, 1.0
	v_mov_b64_e32 v[8:9], v[0:1]
	s_and_saveexec_b64 s[44:45], vcc
	s_cbranch_execz .LBB0_454
	v_mov_b32_e32 v2, v1
	v_mov_b32_e32 v3, v1
	v_mov_b32_e32 v0, v1
	v_mov_b64_e32 v[10:11], v[2:3]
	v_cmp_gt_i32_e32 vcc, s37, v43
	v_mov_b64_e32 v[8:9], v[0:1]
	s_and_saveexec_b64 s[64:65], vcc
	s_cbranch_execz .LBB0_444
	v_mad_i64_i32 v[2:3], s[66:67], v56, s37, 0
	v_lshl_add_u64 v[2:3], v[2:3], 2, s[0:1]
	v_lshl_add_u64 v[2:3], s[42:43], 2, v[2:3]
	v_lshlrev_b32_e32 v0, 2, v41
	v_lshl_add_u64 v[2:3], v[2:3], 0, v[0:1]
	global_load_dwordx4 v[8:11], v[2:3], off
	s_cmp_lt_i32 s70, 64
	s_cbranch_scc1 .Lc3_skip7
	s_and_b32 s98, s37, 63
	s_cmp_lg_u32 s98, 0
	s_cbranch_scc1 .Lc3_skip7
	s_lshl_b32 s98, s37, 7
	v_add_co_u32_e32 v70, vcc, s98, v2
	s_nop 1
	v_addc_co_u32_e32 v71, vcc, 0, v3, vcc
	s_cmp_lg_u32 s39, 0
	s_cbranch_scc1 .Lc3_pf7
	v_mov_b32_e32 v42, 1.0
	v_mov_b32_e32 v52, 1.0
	global_load_dwordx4 v[24:27], v[70:71], off
	s_cmp_lg_u64 s[34:35], 0
	s_cbranch_scc0 .Lc3_ns7
	v_mov_b32_e32 v67, 0
	v_mov_b32_e32 v66, v56
	v_lshl_add_u64 v[68:69], v[66:67], 2, s[6:7]
	global_load_dword v42, v[68:69], off
	global_load_dword v52, v[68:69], off offset:128
	s_branch .Lc3_fin7

.LBB0_918:
	s_add_i32 s0, s64, 63
	s_lshr_b32 s67, s0, 6
	s_add_i32 s0, s70, 63
	s_ashr_i32 s42, s0, 6
	s_mul_i32 s0, s69, 37
	s_add_i32 s0, s0, s68
	s_ashr_i32 s43, s0, 31
	s_abs_i32 s0, s0
	v_readlane_b32 s1, v252, 1
	s_mul_hi_u32 s1, s0, s1
	v_readlane_b32 s4, v252, 0
	s_mul_i32 s1, s1, s4
	s_sub_i32 s0, s0, s1
	s_sub_i32 s1, s0, s4
	s_cmp_ge_u32 s0, s4
	s_cselect_b32 s0, s1, s0
	s_sub_i32 s1, s0, s4
	s_cmp_ge_u32 s0, s4
	s_cselect_b32 s0, s1, s0
	s_xor_b32 s44, s0, s43
	s_sub_i32 s76, s44, s43
	s_mul_i32 s67, s67, s42
	s_cmp_lg_u64 s[30:31], 0
	s_cselect_b64 s[0:1], -1, 0
	s_cmp_lt_i32 s76, s67
	s_cselect_b64 s[4:5], -1, 0
	s_and_b64 vcc, exec, s[4:5]
	s_cbranch_vccz .LBB0_963
	s_abs_i32 s36, s42
	v_cvt_f32_u32_e32 v0, s36
	s_sub_i32 s39, 0, s36
	s_abs_i32 s38, s76
	s_xor_b32 s37, s76, s42
	v_rcp_iflag_f32_e32 v0, v0
	s_ashr_i32 s37, s37, 31
	v_mov_b32_e32 v2, v202
	v_mul_f32_e32 v0, 0x4f7ffffe, v0
	v_cvt_u32_f32_e32 v0, v0
	v_ashrrev_i32_e32 v3, 4, v2
	v_mov_b32_e32 v46, 1.0
	v_readfirstlane_b32 s40, v0
	s_mul_i32 s39, s39, s40
	s_mul_hi_u32 s39, s40, s39
	s_add_i32 s40, s40, s39
	s_mul_hi_u32 s39, s38, s40
	s_mul_i32 s40, s39, s36
	s_sub_i32 s38, s38, s40
	s_add_i32 s41, s39, 1
	s_sub_i32 s40, s38, s36
	s_cmp_ge_u32 s38, s36
	s_cselect_b32 s39, s41, s39
	s_cselect_b32 s38, s40, s38
	s_add_i32 s40, s39, 1
	s_cmp_ge_u32 s38, s36
	s_cselect_b32 s36, s40, s39
	s_xor_b32 s36, s36, s37
	s_sub_i32 s37, s36, s37
	s_mul_i32 s36, s37, s42
	s_sub_i32 s36, s76, s36
	v_lshlrev_b32_e32 v0, 2, v2
	v_lshl_add_u32 v56, s37, 6, v3
	v_mov_b32_e32 v2, v1
	v_mov_b32_e32 v3, v1
	s_lshl_b32 s36, s36, 6
	v_and_b32_e32 v41, 60, v0
	v_mov_b32_e32 v0, v1
	v_mov_b64_e32 v[22:23], v[2:3]
	v_or_b32_e32 v43, s36, v41
	s_ashr_i32 s37, s36, 31
	v_cmp_gt_i32_e32 vcc, s64, v56
	v_mov_b64_e32 v[20:21], v[0:1]
	s_and_saveexec_b64 s[38:39], vcc
	s_cbranch_execz .LBB0_929
	v_mov_b32_e32 v2, v1
	v_mov_b32_e32 v3, v1
	v_mov_b32_e32 v0, v1
	v_mov_b64_e32 v[22:23], v[2:3]
	v_cmp_gt_i32_e32 vcc, s70, v43
	v_mov_b64_e32 v[20:21], v[0:1]
	s_and_saveexec_b64 s[40:41], vcc
	s_cbranch_execz .LBB0_922
	v_mad_i64_i32 v[2:3], s[78:79], v56, s70, 0
	v_lshl_add_u64 v[2:3], v[2:3], 2, s[10:11]
	v_lshl_add_u64 v[2:3], s[36:37], 2, v[2:3]
	v_lshlrev_b32_e32 v0, 2, v41
	v_lshl_add_u64 v[2:3], v[2:3], 0, v[0:1]
	global_load_dwordx4 v[20:23], v[2:3], off
	s_add_i32 s100, s101, 1
	s_min_u32 s100, s100, 3
	s_mov_b32 s101, 0
	s_cmp_lt_i32 s64, 64
	s_cbranch_scc1 .Lc3_skip8
	s_and_b32 s98, s70, 63
	s_cmp_lg_u32 s98, 0
	s_cbranch_scc1 .Lc3_skip8
	s_lshl_b32 s98, s70, 7
	v_add_co_u32_e32 v70, vcc, s98, v2
	s_nop 1
	v_addc_co_u32_e32 v71, vcc, 0, v3, vcc
	s_cmp_lg_u32 s72, 0
	s_cbranch_scc1 .Lc3_pf8
	v_mov_b32_e32 v46, 1.0
	v_mov_b32_e32 v52, 1.0
	global_load_dwordx4 v[36:39], v[70:71], off
	s_cmp_lg_u64 s[0:1], 0
	s_cbranch_scc0 .Lc3_ns8
	v_mov_b32_e32 v67, 0
	v_mov_b32_e32 v66, v56
	v_lshl_add_u64 v[68:69], v[66:67], 2, s[30:31]
	global_load_dword v46, v[68:69], off
	global_load_dword v52, v[68:69], off offset:128
	s_branch .Lc3_fin8

.Lc3_fin8:
	s_mov_b32 s101, s100
	s_or_b64 exec, exec, s[40:41]
	s_or_b64 exec, exec, s[38:39]
	s_branch .Lc3_end8

.LBB0_940:
	s_add_i32 s45, s45, s28
	s_add_i32 s100, s101, 1
	s_min_u32 s100, s100, 3
	s_mov_b32 s101, 0
	s_cmp_ge_i32 s45, s67
	s_cbranch_scc1 .LBB0_985
.LBB0_941:
	s_abs_i32 s36, s42
	s_waitcnt vmcnt(0)
	v_cvt_f32_u32_e32 v0, s36
	s_sub_i32 s39, 0, s36
	s_abs_i32 s38, s45
	s_xor_b32 s37, s45, s42
	v_rcp_iflag_f32_e32 v0, v0
	s_ashr_i32 s37, s37, 31
	v_mov_b32_e32 v2, v202
	v_mul_f32_e32 v0, 0x4f7ffffe, v0
	v_cvt_u32_f32_e32 v0, v0
	v_ashrrev_i32_e32 v3, 4, v2
	v_mov_b32_e32 v40, 1.0
	v_readfirstlane_b32 s40, v0
	s_mul_i32 s39, s39, s40
	s_mul_hi_u32 s39, s40, s39
	s_add_i32 s40, s40, s39
	s_mul_hi_u32 s39, s38, s40
	s_mul_i32 s40, s39, s36
	s_sub_i32 s38, s38, s40
	s_add_i32 s41, s39, 1
	s_sub_i32 s40, s38, s36
	s_cmp_ge_u32 s38, s36
	s_cselect_b32 s39, s41, s39
	s_cselect_b32 s38, s40, s38
	s_add_i32 s40, s39, 1
	s_cmp_ge_u32 s38, s36
	s_cselect_b32 s36, s40, s39
	s_xor_b32 s36, s36, s37
	s_sub_i32 s37, s36, s37
	s_mul_i32 s36, s37, s42
	s_sub_i32 s36, s45, s36
	v_lshlrev_b32_e32 v0, 2, v2
	v_lshl_add_u32 v56, s37, 6, v3
	v_mov_b32_e32 v2, v1
	v_mov_b32_e32 v3, v1
	s_lshl_b32 s36, s36, 6
	v_and_b32_e32 v41, 60, v0
	v_mov_b32_e32 v0, v1
	v_mov_b64_e32 v[14:15], v[2:3]
	v_or_b32_e32 v43, s36, v41
	s_ashr_i32 s37, s36, 31
	v_cmp_gt_i32_e32 vcc, s64, v56
	v_mov_b64_e32 v[12:13], v[0:1]
	s_and_saveexec_b64 s[38:39], vcc
	s_cbranch_execz .LBB0_951
	v_mov_b32_e32 v2, v1
	v_mov_b32_e32 v3, v1
	v_mov_b32_e32 v0, v1
	v_mov_b64_e32 v[14:15], v[2:3]
	v_cmp_gt_i32_e32 vcc, s70, v43
	v_mov_b64_e32 v[12:13], v[0:1]
	s_and_saveexec_b64 s[40:41], vcc
	s_cbranch_execz .LBB0_944
	v_mad_i64_i32 v[2:3], s[78:79], v56, s70, 0
	v_lshl_add_u64 v[2:3], v[2:3], 2, s[10:11]
	v_lshl_add_u64 v[2:3], s[36:37], 2, v[2:3]
	v_lshlrev_b32_e32 v0, 2, v41
	v_lshl_add_u64 v[2:3], v[2:3], 0, v[0:1]
	global_load_dwordx4 v[12:15], v[2:3], off
	s_cmp_lt_i32 s64, 64
	s_cbranch_scc1 .Lc3_skip9
	s_and_b32 s98, s70, 63
	s_cmp_lg_u32 s98, 0
	s_cbranch_scc1 .Lc3_skip9
	s_lshl_b32 s98, s70, 7
	v_add_co_u32_e32 v70, vcc, s98, v2
	s_nop 1
	v_addc_co_u32_e32 v71, vcc, 0, v3, vcc
	s_cmp_lg_u32 s72, 0
	s_cbranch_scc1 .Lc3_pf9
	v_mov_b32_e32 v40, 1.0
	v_mov_b32_e32 v48, 1.0
	global_load_dwordx4 v[28:31], v[70:71], off
	s_cmp_lg_u64 s[0:1], 0
	s_cbranch_scc0 .Lc3_ns9
	v_mov_b32_e32 v67, 0
	v_mov_b32_e32 v66, v56
	v_lshl_add_u64 v[68:69], v[66:67], 2, s[30:31]
	global_load_dword v40, v[68:69], off
	global_load_dword v48, v[68:69], off offset:128
	s_branch .Lc3_fin9

.LBB0_963:
	s_add_i32 s45, s76, s28
	s_add_i32 s100, s101, 1
	s_min_u32 s100, s100, 3
	s_mov_b32 s101, 0
	s_cmp_ge_i32 s45, s67
	s_cbranch_scc1 .LBB0_940
.LBB0_964:
	s_abs_i32 s36, s42
	s_waitcnt vmcnt(0)
	v_cvt_f32_u32_e32 v0, s36
	s_sub_i32 s39, 0, s36
	s_abs_i32 s38, s45
	s_xor_b32 s37, s45, s42
	v_rcp_iflag_f32_e32 v0, v0
	s_ashr_i32 s37, s37, 31
	v_mov_b32_e32 v2, v202
	v_mul_f32_e32 v0, 0x4f7ffffe, v0
	v_cvt_u32_f32_e32 v0, v0
	v_ashrrev_i32_e32 v3, 4, v2
	v_mov_b32_e32 v44, 1.0
	v_readfirstlane_b32 s40, v0
	s_mul_i32 s39, s39, s40
	s_mul_hi_u32 s39, s40, s39
	s_add_i32 s40, s40, s39
	s_mul_hi_u32 s39, s38, s40
	s_mul_i32 s40, s39, s36
	s_sub_i32 s38, s38, s40
	s_add_i32 s41, s39, 1
	s_sub_i32 s40, s38, s36
	s_cmp_ge_u32 s38, s36
	s_cselect_b32 s39, s41, s39
	s_cselect_b32 s38, s40, s38
	s_add_i32 s40, s39, 1
	s_cmp_ge_u32 s38, s36
	s_cselect_b32 s36, s40, s39
	s_xor_b32 s36, s36, s37
	s_sub_i32 s37, s36, s37
	s_mul_i32 s36, s37, s42
	s_sub_i32 s36, s45, s36
	v_lshlrev_b32_e32 v0, 2, v2
	v_lshl_add_u32 v56, s37, 6, v3
	v_mov_b32_e32 v2, v1
	v_mov_b32_e32 v3, v1
	s_lshl_b32 s36, s36, 6
	v_and_b32_e32 v41, 60, v0
	v_mov_b32_e32 v0, v1
	v_mov_b64_e32 v[18:19], v[2:3]
	v_or_b32_e32 v43, s36, v41
	s_ashr_i32 s37, s36, 31
	v_cmp_gt_i32_e32 vcc, s64, v56
	v_mov_b64_e32 v[16:17], v[0:1]
	s_and_saveexec_b64 s[38:39], vcc
	s_cbranch_execz .LBB0_974
	v_mov_b32_e32 v2, v1
	v_mov_b32_e32 v3, v1
	v_mov_b32_e32 v0, v1
	v_mov_b64_e32 v[18:19], v[2:3]
	v_cmp_gt_i32_e32 vcc, s70, v43
	v_mov_b64_e32 v[16:17], v[0:1]
	s_and_saveexec_b64 s[40:41], vcc
	s_cbranch_execz .LBB0_967
	v_mad_i64_i32 v[2:3], s[78:79], v56, s70, 0
	v_lshl_add_u64 v[2:3], v[2:3], 2, s[10:11]
	v_lshl_add_u64 v[2:3], s[36:37], 2, v[2:3]
	v_lshlrev_b32_e32 v0, 2, v41
	v_lshl_add_u64 v[2:3], v[2:3], 0, v[0:1]
	global_load_dwordx4 v[16:19], v[2:3], off
	s_cmp_lt_i32 s64, 64
	s_cbranch_scc1 .Lc3_skip10
	s_and_b32 s98, s70, 63
	s_cmp_lg_u32 s98, 0
	s_cbranch_scc1 .Lc3_skip10
	s_lshl_b32 s98, s70, 7
	v_add_co_u32_e32 v70, vcc, s98, v2
	s_nop 1
	v_addc_co_u32_e32 v71, vcc, 0, v3, vcc
	s_cmp_lg_u32 s72, 0
	s_cbranch_scc1 .Lc3_pf10
	v_mov_b32_e32 v44, 1.0
	v_mov_b32_e32 v50, 1.0
	global_load_dwordx4 v[32:35], v[70:71], off
	s_cmp_lg_u64 s[0:1], 0
	s_cbranch_scc0 .Lc3_ns10
	v_mov_b32_e32 v67, 0
	v_mov_b32_e32 v66, v56
	v_lshl_add_u64 v[68:69], v[66:67], 2, s[30:31]
	global_load_dword v44, v[68:69], off
	global_load_dword v50, v[68:69], off offset:128
	s_branch .Lc3_fin10

.LBB0_986:
	s_abs_i32 s36, s42
	s_waitcnt vmcnt(0)
	v_cvt_f32_u32_e32 v0, s36
	s_sub_i32 s39, 0, s36
	s_abs_i32 s38, s45
	s_xor_b32 s37, s45, s42
	v_rcp_iflag_f32_e32 v0, v0
	s_ashr_i32 s37, s37, 31
	v_mov_b32_e32 v2, v202
	v_mul_f32_e32 v0, 0x4f7ffffe, v0
	v_cvt_u32_f32_e32 v0, v0
	v_ashrrev_i32_e32 v3, 4, v2
	v_mov_b32_e32 v42, 1.0
	v_readfirstlane_b32 s40, v0
	s_mul_i32 s39, s39, s40
	s_mul_hi_u32 s39, s40, s39
	s_add_i32 s40, s40, s39
	s_mul_hi_u32 s39, s38, s40
	s_mul_i32 s40, s39, s36
	s_sub_i32 s38, s38, s40
	s_add_i32 s41, s39, 1
	s_sub_i32 s40, s38, s36
	s_cmp_ge_u32 s38, s36
	s_cselect_b32 s39, s41, s39
	s_cselect_b32 s38, s40, s38
	s_add_i32 s40, s39, 1
	s_cmp_ge_u32 s38, s36
	s_cselect_b32 s36, s40, s39
	s_xor_b32 s36, s36, s37
	s_sub_i32 s37, s36, s37
	s_mul_i32 s36, s37, s42
	s_sub_i32 s36, s45, s36
	v_lshlrev_b32_e32 v0, 2, v2
	v_lshl_add_u32 v56, s37, 6, v3
	v_mov_b32_e32 v2, v1
	v_mov_b32_e32 v3, v1
	s_lshl_b32 s36, s36, 6
	v_and_b32_e32 v41, 60, v0
	v_mov_b32_e32 v0, v1
	s_waitcnt lgkmcnt(0)
	v_mov_b64_e32 v[10:11], v[2:3]
	v_or_b32_e32 v43, s36, v41
	s_ashr_i32 s37, s36, 31
	v_cmp_gt_i32_e32 vcc, s64, v56
	v_mov_b64_e32 v[8:9], v[0:1]
	s_and_saveexec_b64 s[38:39], vcc
	s_cbranch_execz .LBB0_996
	v_mov_b32_e32 v2, v1
	v_mov_b32_e32 v3, v1
	v_mov_b32_e32 v0, v1
	v_mov_b64_e32 v[10:11], v[2:3]
	v_cmp_gt_i32_e32 vcc, s70, v43
	v_mov_b64_e32 v[8:9], v[0:1]
	s_and_saveexec_b64 s[40:41], vcc
	s_cbranch_execz .LBB0_989
	v_mad_i64_i32 v[2:3], s[78:79], v56, s70, 0
	v_lshl_add_u64 v[2:3], v[2:3], 2, s[10:11]
	v_lshl_add_u64 v[2:3], s[36:37], 2, v[2:3]
	v_lshlrev_b32_e32 v0, 2, v41
	v_lshl_add_u64 v[2:3], v[2:3], 0, v[0:1]
	global_load_dwordx4 v[8:11], v[2:3], off
	s_cmp_lt_i32 s64, 64
	s_cbranch_scc1 .Lc3_skip11
	s_and_b32 s98, s70, 63
	s_cmp_lg_u32 s98, 0
	s_cbranch_scc1 .Lc3_skip11
	s_lshl_b32 s98, s70, 7
	v_add_co_u32_e32 v70, vcc, s98, v2
	s_nop 1
	v_addc_co_u32_e32 v71, vcc, 0, v3, vcc
	s_cmp_lg_u32 s72, 0
	s_cbranch_scc1 .Lc3_pf11
	v_mov_b32_e32 v42, 1.0
	v_mov_b32_e32 v54, 1.0
	global_load_dwordx4 v[24:27], v[70:71], off
	s_cmp_lg_u64 s[0:1], 0
	s_cbranch_scc0 .Lc3_ns11
	v_mov_b32_e32 v67, 0
	v_mov_b32_e32 v66, v56
	v_lshl_add_u64 v[68:69], v[66:67], 2, s[30:31]
	global_load_dword v42, v[68:69], off
	global_load_dword v54, v[68:69], off offset:128
	s_branch .Lc3_fin11

.LBB0_1008:
	s_abs_i32 s5, s76
	s_mul_hi_u32 s36, s5, s83
	s_mul_i32 s37, s36, s77
	s_ashr_i32 s4, s76, 31
	s_sub_i32 s5, s5, s37
	s_xor_b32 s4, s4, s78
	s_add_i32 s37, s36, 1
	s_sub_i32 s38, s5, s77
	s_cmp_eq_u32 s101, 0
	s_cbranch_scc1 .Lc3_w0_4
	s_cmp_eq_u32 s101, 1
	s_cbranch_scc1 .Lc3_w4_4
	s_cmp_eq_u32 s101, 2
	s_cbranch_scc1 .Lc3_w8_4
	s_waitcnt vmcnt(12)
	s_branch .Lc3_wd_4

.Lc3_wd_4:
	v_mov_b32_e32 v0, v202
	s_cmp_ge_u32 s5, s77
	s_cselect_b32 s36, s37, s36
	v_ashrrev_i32_e32 v2, 4, v0
	v_lshlrev_b32_e32 v3, 4, v0
	s_cselect_b32 s5, s38, s5
	s_add_i32 s37, s36, 1
	v_and_b32_e32 v3, 0xf0, v3
	v_mul_lo_u32 v2, v2, s3
	s_cmp_ge_u32 s5, s77
	v_add3_u32 v41, 0, v3, v2
	v_pk_mul_f32 v[2:3], v[46:47], v[20:21] op_sel_hi:[0,1]
	s_cselect_b32 s5, s37, s36
	ds_write2_b32 v41, v2, v3 offset1:1
	v_pk_mul_f32 v[2:3], v[46:47], v[22:23] op_sel_hi:[0,1]
	s_xor_b32 s5, s5, s4
	ds_write2_b32 v41, v2, v3 offset0:2 offset1:3
	v_add_u32_e32 v43, 0x2080, v41
	v_pk_mul_f32 v[2:3], v[52:53], v[36:37] op_sel_hi:[0,1]
	s_sub_i32 s36, s5, s4
	ds_write2_b32 v43, v2, v3 offset1:1
	v_add_u32_e32 v41, 0x2088, v41
	v_pk_mul_f32 v[2:3], v[52:53], v[38:39] op_sel_hi:[0,1]
	ds_write2_b32 v41, v2, v3 offset1:1
	v_ashrrev_i32_e32 v2, 3, v0
	s_mul_i32 s4, s79, s36
	s_waitcnt lgkmcnt(0)
	s_barrier
	v_subrev_u32_e32 v3, s4, v2
	v_add_u32_e32 v41, s82, v3
	v_cmp_gt_i32_e32 vcc, s70, v41
	s_and_saveexec_b64 s[4:5], vcc
	s_cbranch_execz .LBB0_1021
	v_lshlrev_b32_e32 v0, 3, v0
	s_lshl_b32 s36, s36, 6
	v_and_b32_e32 v0, 56, v0
	v_or_b32_e32 v3, s36, v0
	v_cmp_gt_i32_e32 vcc, s65, v3
	s_and_b64 exec, exec, vcc
	s_cbranch_execz .LBB0_1021
	v_lshlrev_b32_e32 v45, 2, v2
	v_mul_u32_u24_e32 v2, 0x104, v0
	v_add3_u32 v43, 0, v45, v2
	ds_read2_b32 v[2:3], v43 offset1:65
	ds_read2_b32 v[56:57], v43 offset0:130 offset1:195
	v_add_u32_e32 v43, 0x400, v43
	ds_read2_b32 v[58:59], v43 offset0:4 offset1:69
	ds_read2_b32 v[60:61], v43 offset0:134 offset1:199
	s_mov_b64 s[42:43], -1
	s_mov_b64 s[38:39], 0
	s_cmp_lt_i32 s71, 2
	s_mov_b64 s[40:41], 0
	s_cbranch_scc1 .LBB0_1016
	s_cmp_eq_u32 s71, 2
	s_mov_b64 s[40:41], -1
	s_cbranch_scc0 .LBB0_1013
	v_and_b32_e32 v43, 0x80, v45
	v_lshrrev_b32_e32 v45, 1, v41
	v_and_b32_e32 v45, 0x60, v45
	v_and_b32_e32 v47, 0xffffff1f, v41
	v_or3_b32 v43, v47, v43, v45
	s_mov_b64 s[40:41], 0

.LBB0_1021:
	s_or_b64 exec, exec, s[4:5]
	s_add_i32 s85, s76, s94
	s_waitcnt lgkmcnt(0)
	s_barrier
	s_add_i32 s100, s101, 1
	s_min_u32 s100, s100, 3
	s_mov_b32 s101, 0
	s_cmp_ge_i32 s85, s67
	s_cselect_b64 s[4:5], -1, 0
	s_and_b64 vcc, exec, s[4:5]
	s_cbranch_vccnz .LBB0_1049
	s_abs_i32 s37, s85
	s_mul_hi_u32 s38, s37, s83
	s_mul_i32 s39, s38, s77
	s_ashr_i32 s36, s85, 31
	s_sub_i32 s37, s37, s39
	s_xor_b32 s36, s36, s78
	s_add_i32 s39, s38, 1
	s_sub_i32 s40, s37, s77
	s_cmp_ge_u32 s37, s77
	s_cselect_b32 s38, s39, s38
	s_cselect_b32 s37, s40, s37
	s_add_i32 s39, s38, 1
	s_cmp_ge_u32 s37, s77
	v_mov_b32_e32 v0, v202
	s_cselect_b32 s37, s39, s38
	s_xor_b32 s37, s37, s36
	s_sub_i32 s37, s37, s36
	v_ashrrev_i32_e32 v2, 4, v0
	v_lshlrev_b32_e32 v0, 2, v0
	s_mul_i32 s36, s84, s37
	v_and_b32_e32 v41, 60, v0
	v_lshl_add_u32 v56, s37, 6, v2
	s_mul_i32 s37, s79, s37
	s_add_i32 s38, s29, s82
	v_subrev_u32_e32 v0, s37, v41
	v_mov_b32_e32 v2, v1
	v_mov_b32_e32 v3, v1
	s_add_i32 s36, s38, s36
	v_add_u32_e32 v43, s38, v0
	v_mov_b32_e32 v0, v1
	v_mov_b64_e32 v[22:23], v[2:3]
	s_ashr_i32 s37, s36, 31
	v_cmp_gt_i32_e32 vcc, s64, v56
	v_mov_b32_e32 v46, 1.0
	v_mov_b64_e32 v[20:21], v[0:1]
	s_and_saveexec_b64 s[38:39], vcc
	s_cbranch_execz .LBB0_1035
	v_mov_b32_e32 v2, v1
	v_mov_b32_e32 v3, v1
	v_mov_b32_e32 v0, v1
	v_mov_b64_e32 v[22:23], v[2:3]
	v_cmp_gt_i32_e32 vcc, s70, v43
	v_mov_b64_e32 v[20:21], v[0:1]
	s_and_saveexec_b64 s[40:41], vcc
	s_cbranch_execz .LBB0_1025
	v_mad_i64_i32 v[2:3], s[42:43], v56, s70, 0
	v_lshl_add_u64 v[2:3], v[2:3], 2, s[10:11]
	v_lshl_add_u64 v[2:3], s[36:37], 2, v[2:3]
	v_lshlrev_b32_e32 v0, 2, v41
	v_lshl_add_u64 v[2:3], v[2:3], 0, v[0:1]
	global_load_dwordx4 v[20:23], v[2:3], off
	s_cmp_lt_i32 s64, 64
	s_cbranch_scc1 .Lc3_skip12
	s_and_b32 s98, s70, 63
	s_cmp_lg_u32 s98, 0
	s_cbranch_scc1 .Lc3_skip12
	s_lshl_b32 s98, s70, 7
	v_add_co_u32_e32 v70, vcc, s98, v2
	s_nop 1
	v_addc_co_u32_e32 v71, vcc, 0, v3, vcc
	s_cmp_lg_u32 s72, 0
	s_cbranch_scc1 .Lc3_pf12
	v_mov_b32_e32 v46, 1.0
	v_mov_b32_e32 v52, 1.0
	global_load_dwordx4 v[36:39], v[70:71], off
	s_cmp_lg_u64 s[0:1], 0
	s_cbranch_scc0 .Lc3_ns12
	v_mov_b32_e32 v67, 0
	v_mov_b32_e32 v66, v56
	v_lshl_add_u64 v[68:69], v[66:67], 2, s[30:31]
	global_load_dword v46, v[68:69], off
	global_load_dword v52, v[68:69], off offset:128
	s_branch .Lc3_fin12

.Lc3_end12:
.LBB0_1049:
	s_add_i32 s36, s28, s76
	s_cmp_ge_i32 s36, s67
	s_cbranch_scc1 .LBB0_1091
	s_ashr_i32 s37, s36, 31
	s_abs_i32 s36, s36
	s_mul_hi_u32 s38, s36, s83
	s_mul_i32 s39, s38, s77
	s_sub_i32 s36, s36, s39
	s_xor_b32 s37, s37, s78
	s_add_i32 s39, s38, 1
	s_sub_i32 s40, s36, s77
	s_cmp_eq_u32 s101, 0
	s_cbranch_scc1 .Lc3_w0_5
	s_cmp_eq_u32 s101, 1
	s_cbranch_scc1 .Lc3_w4_5
	s_cmp_eq_u32 s101, 2
	s_cbranch_scc1 .Lc3_w8_5
	s_waitcnt vmcnt(12)
	s_branch .Lc3_wd_5

.Lc3_wd_5:
	v_mov_b32_e32 v0, v202
	s_cmp_ge_u32 s36, s77
	s_cselect_b32 s38, s39, s38
	v_ashrrev_i32_e32 v2, 4, v0
	v_lshlrev_b32_e32 v3, 4, v0
	s_cselect_b32 s36, s40, s36
	s_add_i32 s39, s38, 1
	v_and_b32_e32 v3, 0xf0, v3
	v_mul_lo_u32 v2, v2, s3
	s_cmp_ge_u32 s36, s77
	v_add3_u32 v41, 0, v3, v2
	v_pk_mul_f32 v[2:3], v[44:45], v[16:17] op_sel_hi:[0,1]
	s_cselect_b32 s36, s39, s38
	ds_write2_b32 v41, v2, v3 offset1:1
	v_pk_mul_f32 v[2:3], v[44:45], v[18:19] op_sel_hi:[0,1]
	s_xor_b32 s36, s36, s37
	ds_write2_b32 v41, v2, v3 offset0:2 offset1:3
	v_add_u32_e32 v43, 0x2080, v41
	v_pk_mul_f32 v[2:3], v[50:51], v[32:33] op_sel_hi:[0,1]
	s_sub_i32 s38, s36, s37
	ds_write2_b32 v43, v2, v3 offset1:1
	v_add_u32_e32 v41, 0x2088, v41
	v_pk_mul_f32 v[2:3], v[50:51], v[34:35] op_sel_hi:[0,1]
	ds_write2_b32 v41, v2, v3 offset1:1
	v_ashrrev_i32_e32 v2, 3, v0
	s_mul_i32 s36, s79, s38
	s_waitcnt lgkmcnt(0)
	s_barrier
	v_subrev_u32_e32 v3, s36, v2
	s_add_i32 s36, s80, s82
	v_add_u32_e32 v41, s36, v3
	v_cmp_gt_i32_e32 vcc, s70, v41
	s_and_saveexec_b64 s[36:37], vcc
	s_cbranch_execz .LBB0_1063
	v_lshlrev_b32_e32 v0, 3, v0
	s_lshl_b32 s38, s38, 6
	v_and_b32_e32 v0, 56, v0
	v_or_b32_e32 v3, s38, v0
	v_cmp_gt_i32_e32 vcc, s65, v3
	s_and_b64 exec, exec, vcc
	s_cbranch_execz .LBB0_1063
	v_lshlrev_b32_e32 v45, 2, v2
	v_mul_u32_u24_e32 v2, 0x104, v0
	v_add3_u32 v43, 0, v45, v2
	ds_read2_b32 v[2:3], v43 offset1:65
	ds_read2_b32 v[56:57], v43 offset0:130 offset1:195
	v_add_u32_e32 v43, 0x400, v43
	ds_read2_b32 v[58:59], v43 offset0:4 offset1:69
	ds_read2_b32 v[60:61], v43 offset0:134 offset1:199
	s_mov_b64 s[44:45], -1
	s_mov_b64 s[40:41], 0
	s_cmp_lt_i32 s71, 2
	s_mov_b64 s[42:43], 0
	s_cbranch_scc1 .LBB0_1058
	s_cmp_eq_u32 s71, 2
	s_mov_b64 s[42:43], -1
	s_cbranch_scc0 .LBB0_1055
	v_and_b32_e32 v43, 0x80, v45
	v_lshrrev_b32_e32 v45, 1, v41
	v_and_b32_e32 v45, 0x60, v45
	v_and_b32_e32 v47, 0xffffff1f, v41
	v_or3_b32 v43, v47, v43, v45
	s_mov_b64 s[42:43], 0

.LBB0_1063:
	s_or_b64 exec, exec, s[36:37]
	s_waitcnt lgkmcnt(0)
	s_barrier
	s_mul_i32 s36, s28, 5
	s_add_i32 s36, s36, s76
	s_add_i32 s100, s101, 1
	s_min_u32 s100, s100, 3
	s_mov_b32 s101, 0
	s_cmp_ge_i32 s36, s67
	s_cbranch_scc1 .LBB0_1091
	s_ashr_i32 s37, s36, 31
	s_abs_i32 s36, s36
	s_mul_hi_u32 s38, s36, s83
	s_mul_i32 s39, s38, s77
	s_sub_i32 s36, s36, s39
	s_xor_b32 s37, s37, s78
	s_add_i32 s39, s38, 1
	s_sub_i32 s40, s36, s77
	s_cmp_ge_u32 s36, s77
	s_cselect_b32 s38, s39, s38
	s_cselect_b32 s36, s40, s36
	s_add_i32 s39, s38, 1
	s_cmp_ge_u32 s36, s77
	v_mov_b32_e32 v0, v202
	s_cselect_b32 s36, s39, s38
	s_xor_b32 s36, s36, s37
	s_sub_i32 s37, s36, s37
	v_ashrrev_i32_e32 v2, 4, v0
	v_lshlrev_b32_e32 v0, 2, v0
	s_mul_i32 s36, s84, s37
	s_mul_i32 s38, s28, 0x140
	v_and_b32_e32 v41, 60, v0
	v_lshl_add_u32 v56, s37, 6, v2
	s_mul_i32 s37, s79, s37
	s_add_i32 s38, s38, s82
	v_subrev_u32_e32 v0, s37, v41
	v_mov_b32_e32 v2, v1
	v_mov_b32_e32 v3, v1
	s_add_i32 s36, s38, s36
	v_add_u32_e32 v43, s38, v0
	v_mov_b32_e32 v0, v1
	v_mov_b64_e32 v[18:19], v[2:3]
	s_ashr_i32 s37, s36, 31
	v_cmp_gt_i32_e32 vcc, s64, v56
	v_mov_b32_e32 v44, 1.0
	v_mov_b64_e32 v[16:17], v[0:1]
	s_and_saveexec_b64 s[38:39], vcc
	s_cbranch_execz .LBB0_1077
	v_mov_b32_e32 v2, v1
	v_mov_b32_e32 v3, v1
	v_mov_b32_e32 v0, v1
	v_mov_b64_e32 v[18:19], v[2:3]
	v_cmp_gt_i32_e32 vcc, s70, v43
	v_mov_b64_e32 v[16:17], v[0:1]
	s_and_saveexec_b64 s[40:41], vcc
	s_cbranch_execz .LBB0_1067
	v_mad_i64_i32 v[2:3], s[42:43], v56, s70, 0
	v_lshl_add_u64 v[2:3], v[2:3], 2, s[10:11]
	v_lshl_add_u64 v[2:3], s[36:37], 2, v[2:3]
	v_lshlrev_b32_e32 v0, 2, v41
	v_lshl_add_u64 v[2:3], v[2:3], 0, v[0:1]
	global_load_dwordx4 v[16:19], v[2:3], off
	s_cmp_lt_i32 s64, 64
	s_cbranch_scc1 .Lc3_skip13
	s_and_b32 s98, s70, 63
	s_cmp_lg_u32 s98, 0
	s_cbranch_scc1 .Lc3_skip13
	s_lshl_b32 s98, s70, 7
	v_add_co_u32_e32 v70, vcc, s98, v2
	s_nop 1
	v_addc_co_u32_e32 v71, vcc, 0, v3, vcc
	s_cmp_lg_u32 s72, 0
	s_cbranch_scc1 .Lc3_pf13
	v_mov_b32_e32 v44, 1.0
	v_mov_b32_e32 v50, 1.0
	global_load_dwordx4 v[32:35], v[70:71], off
	s_cmp_lg_u64 s[0:1], 0
	s_cbranch_scc0 .Lc3_ns13
	v_mov_b32_e32 v67, 0
	v_mov_b32_e32 v66, v56
	v_lshl_add_u64 v[68:69], v[66:67], 2, s[30:31]
	global_load_dword v44, v[68:69], off
	global_load_dword v50, v[68:69], off offset:128
	s_branch .Lc3_fin13

.Lc3_end13:
.LBB0_1091:
	s_add_i32 s36, s95, s76
	s_cmp_ge_i32 s36, s67
	s_cbranch_scc1 .LBB0_1133
	s_ashr_i32 s37, s36, 31
	s_abs_i32 s36, s36
	s_mul_hi_u32 s38, s36, s83
	s_mul_i32 s39, s38, s77
	s_sub_i32 s36, s36, s39
	s_cmp_eq_u32 s101, 0
	s_cbranch_scc1 .Lc3_w0_6
	s_cmp_eq_u32 s101, 1
	s_cbranch_scc1 .Lc3_w4_6
	s_cmp_eq_u32 s101, 2
	s_cbranch_scc1 .Lc3_w8_6
	s_waitcnt vmcnt(12)
	s_branch .Lc3_wd_6

.Lc3_wd_6:
	v_mov_b32_e32 v0, v202
	s_xor_b32 s37, s37, s78
	s_add_i32 s39, s38, 1
	s_sub_i32 s40, s36, s77
	s_cmp_ge_u32 s36, s77
	v_ashrrev_i32_e32 v2, 4, v0
	v_lshlrev_b32_e32 v3, 4, v0
	s_cselect_b32 s38, s39, s38
	v_and_b32_e32 v3, 0xf0, v3
	v_mul_lo_u32 v2, v2, s3
	s_cselect_b32 s36, s40, s36
	s_add_i32 s39, s38, 1
	v_add3_u32 v41, 0, v3, v2
	s_cmp_ge_u32 s36, s77
	v_pk_mul_f32 v[2:3], v[40:41], v[12:13] op_sel_hi:[0,1]
	s_cselect_b32 s36, s39, s38
	ds_write2_b32 v41, v2, v3 offset1:1
	v_pk_mul_f32 v[2:3], v[40:41], v[14:15] op_sel_hi:[0,1]
	s_xor_b32 s36, s36, s37
	ds_write2_b32 v41, v2, v3 offset0:2 offset1:3
	v_add_u32_e32 v43, 0x2080, v41
	v_pk_mul_f32 v[2:3], v[48:49], v[28:29] op_sel_hi:[0,1]
	s_sub_i32 s38, s36, s37
	ds_write2_b32 v43, v2, v3 offset1:1
	v_add_u32_e32 v41, 0x2088, v41
	v_pk_mul_f32 v[2:3], v[48:49], v[30:31] op_sel_hi:[0,1]
	ds_write2_b32 v41, v2, v3 offset1:1
	v_ashrrev_i32_e32 v2, 3, v0
	s_mul_i32 s36, s79, s38
	s_waitcnt lgkmcnt(0)
	s_barrier
	v_subrev_u32_e32 v3, s36, v2
	s_add_i32 s36, s81, s82
	v_add_u32_e32 v41, s36, v3
	v_cmp_gt_i32_e32 vcc, s70, v41
	s_and_saveexec_b64 s[36:37], vcc
	s_cbranch_execz .LBB0_1105
	v_lshlrev_b32_e32 v0, 3, v0
	s_lshl_b32 s38, s38, 6
	v_and_b32_e32 v0, 56, v0
	v_or_b32_e32 v3, s38, v0
	v_cmp_gt_i32_e32 vcc, s65, v3
	s_and_b64 exec, exec, vcc
	s_cbranch_execz .LBB0_1105
	v_lshlrev_b32_e32 v45, 2, v2
	v_mul_u32_u24_e32 v2, 0x104, v0
	v_add3_u32 v43, 0, v45, v2
	ds_read2_b32 v[2:3], v43 offset1:65
	ds_read2_b32 v[56:57], v43 offset0:130 offset1:195
	v_add_u32_e32 v43, 0x400, v43
	ds_read2_b32 v[58:59], v43 offset0:4 offset1:69
	ds_read2_b32 v[60:61], v43 offset0:134 offset1:199
	s_mov_b64 s[44:45], -1
	s_mov_b64 s[40:41], 0
	s_cmp_lt_i32 s71, 2
	s_mov_b64 s[42:43], 0
	s_cbranch_scc1 .LBB0_1100
	s_cmp_eq_u32 s71, 2
	s_mov_b64 s[42:43], -1
	s_cbranch_scc0 .LBB0_1097
	v_and_b32_e32 v43, 0x80, v45
	v_lshrrev_b32_e32 v45, 1, v41
	v_and_b32_e32 v45, 0x60, v45
	v_and_b32_e32 v47, 0xffffff1f, v41
	v_or3_b32 v43, v47, v43, v45
	s_mov_b64 s[42:43], 0

.LBB0_1105:
	s_or_b64 exec, exec, s[36:37]
	s_waitcnt lgkmcnt(0)
	s_barrier
	s_mul_i32 s36, s28, 6
	s_add_i32 s36, s36, s76
	s_add_i32 s100, s101, 1
	s_min_u32 s100, s100, 3
	s_mov_b32 s101, 0
	s_cmp_ge_i32 s36, s67
	s_cbranch_scc1 .LBB0_1133
	s_ashr_i32 s37, s36, 31
	s_abs_i32 s36, s36
	s_mul_hi_u32 s38, s36, s83
	s_mul_i32 s39, s38, s77
	s_sub_i32 s36, s36, s39
	s_xor_b32 s37, s37, s78
	s_add_i32 s39, s38, 1
	s_sub_i32 s40, s36, s77
	s_cmp_ge_u32 s36, s77
	s_cselect_b32 s38, s39, s38
	s_cselect_b32 s36, s40, s36
	s_add_i32 s39, s38, 1
	s_cmp_ge_u32 s36, s77
	v_mov_b32_e32 v0, v202
	s_cselect_b32 s36, s39, s38
	s_xor_b32 s36, s36, s37
	s_sub_i32 s37, s36, s37
	v_ashrrev_i32_e32 v2, 4, v0
	v_lshlrev_b32_e32 v0, 2, v0
	s_mul_i32 s36, s84, s37
	s_mul_i32 s38, s28, 0x180
	v_and_b32_e32 v41, 60, v0
	v_lshl_add_u32 v56, s37, 6, v2
	s_mul_i32 s37, s79, s37
	s_add_i32 s38, s38, s82
	v_subrev_u32_e32 v0, s37, v41
	v_mov_b32_e32 v2, v1
	v_mov_b32_e32 v3, v1
	s_add_i32 s36, s38, s36
	v_add_u32_e32 v43, s38, v0
	v_mov_b32_e32 v0, v1
	v_mov_b64_e32 v[14:15], v[2:3]
	s_ashr_i32 s37, s36, 31
	v_cmp_gt_i32_e32 vcc, s64, v56
	v_mov_b32_e32 v40, 1.0
	v_mov_b64_e32 v[12:13], v[0:1]
	s_and_saveexec_b64 s[38:39], vcc
	s_cbranch_execz .LBB0_1119
	v_mov_b32_e32 v2, v1
	v_mov_b32_e32 v3, v1
	v_mov_b32_e32 v0, v1
	v_mov_b64_e32 v[14:15], v[2:3]
	v_cmp_gt_i32_e32 vcc, s70, v43
	v_mov_b64_e32 v[12:13], v[0:1]
	s_and_saveexec_b64 s[40:41], vcc
	s_cbranch_execz .LBB0_1109
	v_mad_i64_i32 v[2:3], s[42:43], v56, s70, 0
	v_lshl_add_u64 v[2:3], v[2:3], 2, s[10:11]
	v_lshl_add_u64 v[2:3], s[36:37], 2, v[2:3]
	v_lshlrev_b32_e32 v0, 2, v41
	v_lshl_add_u64 v[2:3], v[2:3], 0, v[0:1]
	global_load_dwordx4 v[12:15], v[2:3], off
	s_cmp_lt_i32 s64, 64
	s_cbranch_scc1 .Lc3_skip14
	s_and_b32 s98, s70, 63
	s_cmp_lg_u32 s98, 0
	s_cbranch_scc1 .Lc3_skip14
	s_lshl_b32 s98, s70, 7
	v_add_co_u32_e32 v70, vcc, s98, v2
	s_nop 1
	v_addc_co_u32_e32 v71, vcc, 0, v3, vcc
	s_cmp_lg_u32 s72, 0
	s_cbranch_scc1 .Lc3_pf14
	v_mov_b32_e32 v40, 1.0
	v_mov_b32_e32 v48, 1.0
	global_load_dwordx4 v[28:31], v[70:71], off
	s_cmp_lg_u64 s[0:1], 0
	s_cbranch_scc0 .Lc3_ns14
	v_mov_b32_e32 v67, 0
	v_mov_b32_e32 v66, v56
	v_lshl_add_u64 v[68:69], v[66:67], 2, s[30:31]
	global_load_dword v40, v[68:69], off
	global_load_dword v48, v[68:69], off offset:128
	s_branch .Lc3_fin14

.Lc3_end14:
.LBB0_1133:
	s_add_i32 s36, s33, s76
	s_cmp_ge_i32 s36, s67
	s_cbranch_scc1 .LBB0_1175
	s_ashr_i32 s37, s36, 31
	s_abs_i32 s36, s36
	s_mul_hi_u32 s38, s36, s83
	s_mul_i32 s39, s38, s77
	s_sub_i32 s36, s36, s39
	s_xor_b32 s37, s37, s78
	s_add_i32 s39, s38, 1
	s_sub_i32 s40, s36, s77
	s_cmp_eq_u32 s101, 0
	s_cbranch_scc1 .Lc3_w0_7
	s_cmp_eq_u32 s101, 1
	s_cbranch_scc1 .Lc3_w4_7
	s_cmp_eq_u32 s101, 2
	s_cbranch_scc1 .Lc3_w8_7
	s_waitcnt vmcnt(12)
	s_branch .Lc3_wd_7

.Lc3_wd_7:
	v_mov_b32_e32 v0, v202
	s_cmp_ge_u32 s36, s77
	s_cselect_b32 s38, s39, s38
	v_ashrrev_i32_e32 v2, 4, v0
	v_lshlrev_b32_e32 v3, 4, v0
	s_cselect_b32 s36, s40, s36
	s_add_i32 s39, s38, 1
	v_and_b32_e32 v3, 0xf0, v3
	v_mul_lo_u32 v2, v2, s3
	s_cmp_ge_u32 s36, s77
	v_add3_u32 v41, 0, v3, v2
	s_waitcnt lgkmcnt(4)
	v_pk_mul_f32 v[2:3], v[8:9], v[42:43] op_sel_hi:[1,0]
	s_cselect_b32 s36, s39, s38
	ds_write2_b32 v41, v2, v3 offset1:1
	v_pk_mul_f32 v[2:3], v[10:11], v[42:43] op_sel_hi:[1,0]
	s_xor_b32 s36, s36, s37
	ds_write2_b32 v41, v2, v3 offset0:2 offset1:3
	v_add_u32_e32 v43, 0x2080, v41
	v_pk_mul_f32 v[2:3], v[24:25], v[54:55] op_sel_hi:[1,0]
	s_sub_i32 s38, s36, s37
	ds_write2_b32 v43, v2, v3 offset1:1
	v_add_u32_e32 v41, 0x2088, v41
	v_pk_mul_f32 v[2:3], v[26:27], v[54:55] op_sel_hi:[1,0]
	ds_write2_b32 v41, v2, v3 offset1:1
	v_ashrrev_i32_e32 v2, 3, v0
	s_mul_i32 s36, s79, s38
	v_subrev_u32_e32 v3, s36, v2
	s_mul_i32 s36, s28, 0xc0
	s_waitcnt lgkmcnt(0)
	s_barrier
	s_add_i32 s36, s36, s82
	v_add_u32_e32 v41, s36, v3
	v_cmp_gt_i32_e32 vcc, s70, v41
	s_and_saveexec_b64 s[36:37], vcc
	s_cbranch_execz .LBB0_1147
	v_lshlrev_b32_e32 v0, 3, v0
	s_lshl_b32 s38, s38, 6
	v_and_b32_e32 v0, 56, v0
	v_or_b32_e32 v3, s38, v0
	v_cmp_gt_i32_e32 vcc, s65, v3
	s_and_b64 exec, exec, vcc
	s_cbranch_execz .LBB0_1147
	v_lshlrev_b32_e32 v45, 2, v2
	v_mul_u32_u24_e32 v2, 0x104, v0
	v_add3_u32 v43, 0, v45, v2
	ds_read2_b32 v[2:3], v43 offset1:65
	ds_read2_b32 v[56:57], v43 offset0:130 offset1:195
	v_add_u32_e32 v43, 0x400, v43
	ds_read2_b32 v[58:59], v43 offset0:4 offset1:69
	ds_read2_b32 v[60:61], v43 offset0:134 offset1:199
	s_mov_b64 s[44:45], -1
	s_mov_b64 s[40:41], 0
	s_cmp_lt_i32 s71, 2
	s_mov_b64 s[42:43], 0
	s_cbranch_scc1 .LBB0_1142
	s_cmp_eq_u32 s71, 2
	s_mov_b64 s[42:43], -1
	s_cbranch_scc0 .LBB0_1139
	v_and_b32_e32 v43, 0x80, v45
	v_lshrrev_b32_e32 v45, 1, v41
	v_and_b32_e32 v45, 0x60, v45
	v_and_b32_e32 v47, 0xffffff1f, v41
	v_or3_b32 v43, v47, v43, v45
	s_mov_b64 s[42:43], 0

.LBB0_1147:
	s_or_b64 exec, exec, s[36:37]
	s_waitcnt lgkmcnt(0)
	s_barrier
	s_mul_i32 s36, s28, 7
	s_add_i32 s36, s36, s76
	s_add_i32 s100, s101, 1
	s_min_u32 s100, s100, 3
	s_mov_b32 s101, 0
	s_cmp_ge_i32 s36, s67
	s_cbranch_scc1 .LBB0_1175
	s_ashr_i32 s37, s36, 31
	s_abs_i32 s36, s36
	s_mul_hi_u32 s38, s36, s83
	s_mul_i32 s39, s38, s77
	s_sub_i32 s36, s36, s39
	s_xor_b32 s37, s37, s78
	s_add_i32 s39, s38, 1
	s_sub_i32 s40, s36, s77
	s_cmp_ge_u32 s36, s77
	s_cselect_b32 s38, s39, s38
	s_cselect_b32 s36, s40, s36
	s_add_i32 s39, s38, 1
	s_cmp_ge_u32 s36, s77
	v_mov_b32_e32 v0, v202
	s_cselect_b32 s36, s39, s38
	s_xor_b32 s36, s36, s37
	s_sub_i32 s37, s36, s37
	v_ashrrev_i32_e32 v2, 4, v0
	v_lshlrev_b32_e32 v0, 2, v0
	s_mul_i32 s36, s84, s37
	s_mul_i32 s38, s28, 0x1c0
	v_and_b32_e32 v41, 60, v0
	v_lshl_add_u32 v56, s37, 6, v2
	s_mul_i32 s37, s79, s37
	s_add_i32 s38, s38, s82
	v_subrev_u32_e32 v0, s37, v41
	v_mov_b32_e32 v2, v1
	v_mov_b32_e32 v3, v1
	s_add_i32 s36, s38, s36
	v_add_u32_e32 v43, s38, v0
	v_mov_b32_e32 v0, v1
	v_mov_b64_e32 v[10:11], v[2:3]
	s_ashr_i32 s37, s36, 31
	v_cmp_gt_i32_e32 vcc, s64, v56
	v_mov_b32_e32 v42, 1.0
	v_mov_b64_e32 v[8:9], v[0:1]
	s_and_saveexec_b64 s[38:39], vcc
	s_cbranch_execz .LBB0_1161
	v_mov_b32_e32 v2, v1
	v_mov_b32_e32 v3, v1
	v_mov_b32_e32 v0, v1
	v_mov_b64_e32 v[10:11], v[2:3]
	v_cmp_gt_i32_e32 vcc, s70, v43
	v_mov_b64_e32 v[8:9], v[0:1]
	s_and_saveexec_b64 s[40:41], vcc
	s_cbranch_execz .LBB0_1151
	v_mad_i64_i32 v[2:3], s[42:43], v56, s70, 0
	v_lshl_add_u64 v[2:3], v[2:3], 2, s[10:11]
	v_lshl_add_u64 v[2:3], s[36:37], 2, v[2:3]
	v_lshlrev_b32_e32 v0, 2, v41
	v_lshl_add_u64 v[2:3], v[2:3], 0, v[0:1]
	global_load_dwordx4 v[8:11], v[2:3], off
	s_cmp_lt_i32 s64, 64
	s_cbranch_scc1 .Lc3_skip15
	s_and_b32 s98, s70, 63
	s_cmp_lg_u32 s98, 0
	s_cbranch_scc1 .Lc3_skip15
	s_lshl_b32 s98, s70, 7
	v_add_co_u32_e32 v70, vcc, s98, v2
	s_nop 1
	v_addc_co_u32_e32 v71, vcc, 0, v3, vcc
	s_cmp_lg_u32 s72, 0
	s_cbranch_scc1 .Lc3_pf15
	v_mov_b32_e32 v42, 1.0
	v_mov_b32_e32 v54, 1.0
	global_load_dwordx4 v[24:27], v[70:71], off
	s_cmp_lg_u64 s[0:1], 0
	s_cbranch_scc0 .Lc3_ns15
	v_mov_b32_e32 v67, 0
	v_mov_b32_e32 v66, v56
	v_lshl_add_u64 v[68:69], v[66:67], 2, s[30:31]
	global_load_dword v42, v[68:69], off
	global_load_dword v54, v[68:69], off offset:128
	s_branch .Lc3_fin15

.LBB0_1270:
	s_add_i32 s30, s64, 63
	s_lshr_b32 s72, s30, 6
	s_add_i32 s30, s68, 63
	s_ashr_i32 s42, s30, 6
	s_mul_i32 s30, s67, 37
	s_add_i32 s30, s30, s66
	s_ashr_i32 s43, s30, 31
	s_abs_i32 s30, s30
	v_readlane_b32 s31, v252, 1
	s_mul_hi_u32 s31, s30, s31
	v_readlane_b32 s34, v252, 0
	s_mul_i32 s31, s31, s34
	s_sub_i32 s30, s30, s31
	s_sub_i32 s31, s30, s34
	s_cmp_ge_u32 s30, s34
	s_cselect_b32 s30, s31, s30
	s_sub_i32 s31, s30, s34
	s_cmp_ge_u32 s30, s34
	s_cselect_b32 s30, s31, s30
	s_xor_b32 s44, s30, s43
	s_sub_i32 s76, s44, s43
	s_mul_i32 s72, s72, s42
	s_cmp_lg_u64 s[8:9], 0
	s_cselect_b64 s[30:31], -1, 0
	s_cmp_lt_i32 s76, s72
	s_cselect_b64 s[34:35], -1, 0
	s_and_b64 vcc, exec, s[34:35]
	s_cbranch_vccz .LBB0_1315
	s_abs_i32 s36, s42
	v_cvt_f32_u32_e32 v0, s36
	s_sub_i32 s39, 0, s36
	s_abs_i32 s38, s76
	s_xor_b32 s37, s76, s42
	v_rcp_iflag_f32_e32 v0, v0
	s_ashr_i32 s37, s37, 31
	v_mov_b32_e32 v2, v202
	v_mul_f32_e32 v0, 0x4f7ffffe, v0
	v_cvt_u32_f32_e32 v0, v0
	v_ashrrev_i32_e32 v3, 4, v2
	v_mov_b32_e32 v46, 1.0
	v_readfirstlane_b32 s40, v0
	s_mul_i32 s39, s39, s40
	s_mul_hi_u32 s39, s40, s39
	s_add_i32 s40, s40, s39
	s_mul_hi_u32 s39, s38, s40
	s_mul_i32 s40, s39, s36
	s_sub_i32 s38, s38, s40
	s_add_i32 s41, s39, 1
	s_sub_i32 s40, s38, s36
	s_cmp_ge_u32 s38, s36
	s_cselect_b32 s39, s41, s39
	s_cselect_b32 s38, s40, s38
	s_add_i32 s40, s39, 1
	s_cmp_ge_u32 s38, s36
	s_cselect_b32 s36, s40, s39
	s_xor_b32 s36, s36, s37
	s_sub_i32 s37, s36, s37
	s_mul_i32 s36, s37, s42
	s_sub_i32 s36, s76, s36
	v_lshlrev_b32_e32 v0, 2, v2
	v_lshl_add_u32 v56, s37, 6, v3
	v_mov_b32_e32 v2, v1
	v_mov_b32_e32 v3, v1
	s_lshl_b32 s36, s36, 6
	v_and_b32_e32 v41, 60, v0
	v_mov_b32_e32 v0, v1
	v_mov_b64_e32 v[22:23], v[2:3]
	v_or_b32_e32 v43, s36, v41
	s_ashr_i32 s37, s36, 31
	v_cmp_gt_i32_e32 vcc, s64, v56
	v_mov_b64_e32 v[20:21], v[0:1]
	s_and_saveexec_b64 s[38:39], vcc
	s_cbranch_execz .LBB0_1281
	v_mov_b32_e32 v2, v1
	v_mov_b32_e32 v3, v1
	v_mov_b32_e32 v0, v1
	v_mov_b64_e32 v[22:23], v[2:3]
	v_cmp_gt_i32_e32 vcc, s68, v43
	v_mov_b64_e32 v[20:21], v[0:1]
	s_and_saveexec_b64 s[40:41], vcc
	s_cbranch_execz .LBB0_1274
	v_mad_i64_i32 v[2:3], s[78:79], v56, s68, 0
	v_lshl_add_u64 v[2:3], v[2:3], 2, s[4:5]
	v_lshl_add_u64 v[2:3], s[36:37], 2, v[2:3]
	v_lshlrev_b32_e32 v0, 2, v41
	v_lshl_add_u64 v[2:3], v[2:3], 0, v[0:1]
	global_load_dwordx4 v[20:23], v[2:3], off
	s_add_i32 s100, s101, 1
	s_min_u32 s100, s100, 3
	s_mov_b32 s101, 0
	s_cmp_lt_i32 s64, 64
	s_cbranch_scc1 .Lc3_skip16
	s_and_b32 s98, s68, 63
	s_cmp_lg_u32 s98, 0
	s_cbranch_scc1 .Lc3_skip16
	s_lshl_b32 s98, s68, 7
	v_add_co_u32_e32 v70, vcc, s98, v2
	s_nop 1
	v_addc_co_u32_e32 v71, vcc, 0, v3, vcc
	s_cmp_lg_u32 s70, 0
	s_cbranch_scc1 .Lc3_pf16
	v_mov_b32_e32 v46, 1.0
	v_mov_b32_e32 v52, 1.0
	global_load_dwordx4 v[36:39], v[70:71], off
	s_cmp_lg_u64 s[30:31], 0
	s_cbranch_scc0 .Lc3_ns16
	v_mov_b32_e32 v67, 0
	v_mov_b32_e32 v66, v56
	v_lshl_add_u64 v[68:69], v[66:67], 2, s[8:9]
	global_load_dword v46, v[68:69], off
	global_load_dword v52, v[68:69], off offset:128
	s_branch .Lc3_fin16

.LBB0_1292:
	s_add_i32 s45, s45, s28
	s_add_i32 s100, s101, 1
	s_min_u32 s100, s100, 3
	s_mov_b32 s101, 0
	s_cmp_ge_i32 s45, s72
	s_cbranch_scc1 .LBB0_1337
.LBB0_1293:
	s_abs_i32 s36, s42
	s_waitcnt vmcnt(0)
	v_cvt_f32_u32_e32 v0, s36
	s_sub_i32 s39, 0, s36
	s_abs_i32 s38, s45
	s_xor_b32 s37, s45, s42
	v_rcp_iflag_f32_e32 v0, v0
	s_ashr_i32 s37, s37, 31
	v_mov_b32_e32 v2, v202
	v_mul_f32_e32 v0, 0x4f7ffffe, v0
	v_cvt_u32_f32_e32 v0, v0
	v_ashrrev_i32_e32 v3, 4, v2
	v_mov_b32_e32 v40, 1.0
	v_readfirstlane_b32 s40, v0
	s_mul_i32 s39, s39, s40
	s_mul_hi_u32 s39, s40, s39
	s_add_i32 s40, s40, s39
	s_mul_hi_u32 s39, s38, s40
	s_mul_i32 s40, s39, s36
	s_sub_i32 s38, s38, s40
	s_add_i32 s41, s39, 1
	s_sub_i32 s40, s38, s36
	s_cmp_ge_u32 s38, s36
	s_cselect_b32 s39, s41, s39
	s_cselect_b32 s38, s40, s38
	s_add_i32 s40, s39, 1
	s_cmp_ge_u32 s38, s36
	s_cselect_b32 s36, s40, s39
	s_xor_b32 s36, s36, s37
	s_sub_i32 s37, s36, s37
	s_mul_i32 s36, s37, s42
	s_sub_i32 s36, s45, s36
	v_lshlrev_b32_e32 v0, 2, v2
	v_lshl_add_u32 v56, s37, 6, v3
	v_mov_b32_e32 v2, v1
	v_mov_b32_e32 v3, v1
	s_lshl_b32 s36, s36, 6
	v_and_b32_e32 v41, 60, v0
	v_mov_b32_e32 v0, v1
	v_mov_b64_e32 v[14:15], v[2:3]
	v_or_b32_e32 v43, s36, v41
	s_ashr_i32 s37, s36, 31
	v_cmp_gt_i32_e32 vcc, s64, v56
	v_mov_b64_e32 v[12:13], v[0:1]
	s_and_saveexec_b64 s[38:39], vcc
	s_cbranch_execz .LBB0_1303
	v_mov_b32_e32 v2, v1
	v_mov_b32_e32 v3, v1
	v_mov_b32_e32 v0, v1
	v_mov_b64_e32 v[14:15], v[2:3]
	v_cmp_gt_i32_e32 vcc, s68, v43
	v_mov_b64_e32 v[12:13], v[0:1]
	s_and_saveexec_b64 s[40:41], vcc
	s_cbranch_execz .LBB0_1296
	v_mad_i64_i32 v[2:3], s[78:79], v56, s68, 0
	v_lshl_add_u64 v[2:3], v[2:3], 2, s[4:5]
	v_lshl_add_u64 v[2:3], s[36:37], 2, v[2:3]
	v_lshlrev_b32_e32 v0, 2, v41
	v_lshl_add_u64 v[2:3], v[2:3], 0, v[0:1]
	global_load_dwordx4 v[12:15], v[2:3], off
	s_cmp_lt_i32 s64, 64
	s_cbranch_scc1 .Lc3_skip17
	s_and_b32 s98, s68, 63
	s_cmp_lg_u32 s98, 0
	s_cbranch_scc1 .Lc3_skip17
	s_lshl_b32 s98, s68, 7
	v_add_co_u32_e32 v70, vcc, s98, v2
	s_nop 1
	v_addc_co_u32_e32 v71, vcc, 0, v3, vcc
	s_cmp_lg_u32 s70, 0
	s_cbranch_scc1 .Lc3_pf17
	v_mov_b32_e32 v40, 1.0
	v_mov_b32_e32 v48, 1.0
	global_load_dwordx4 v[28:31], v[70:71], off
	s_cmp_lg_u64 s[30:31], 0
	s_cbranch_scc0 .Lc3_ns17
	v_mov_b32_e32 v67, 0
	v_mov_b32_e32 v66, v56
	v_lshl_add_u64 v[68:69], v[66:67], 2, s[8:9]
	global_load_dword v40, v[68:69], off
	global_load_dword v48, v[68:69], off offset:128
	s_branch .Lc3_fin17

.LBB0_1315:
	s_add_i32 s45, s76, s28
	s_add_i32 s100, s101, 1
	s_min_u32 s100, s100, 3
	s_mov_b32 s101, 0
	s_cmp_ge_i32 s45, s72
	s_cbranch_scc1 .LBB0_1292
.LBB0_1316:
	s_abs_i32 s36, s42
	s_waitcnt vmcnt(0)
	v_cvt_f32_u32_e32 v0, s36
	s_sub_i32 s39, 0, s36
	s_abs_i32 s38, s45
	s_xor_b32 s37, s45, s42
	v_rcp_iflag_f32_e32 v0, v0
	s_ashr_i32 s37, s37, 31
	v_mov_b32_e32 v2, v202
	v_mul_f32_e32 v0, 0x4f7ffffe, v0
	v_cvt_u32_f32_e32 v0, v0
	v_ashrrev_i32_e32 v3, 4, v2
	v_mov_b32_e32 v44, 1.0
	v_readfirstlane_b32 s40, v0
	s_mul_i32 s39, s39, s40
	s_mul_hi_u32 s39, s40, s39
	s_add_i32 s40, s40, s39
	s_mul_hi_u32 s39, s38, s40
	s_mul_i32 s40, s39, s36
	s_sub_i32 s38, s38, s40
	s_add_i32 s41, s39, 1
	s_sub_i32 s40, s38, s36
	s_cmp_ge_u32 s38, s36
	s_cselect_b32 s39, s41, s39
	s_cselect_b32 s38, s40, s38
	s_add_i32 s40, s39, 1
	s_cmp_ge_u32 s38, s36
	s_cselect_b32 s36, s40, s39
	s_xor_b32 s36, s36, s37
	s_sub_i32 s37, s36, s37
	s_mul_i32 s36, s37, s42
	s_sub_i32 s36, s45, s36
	v_lshlrev_b32_e32 v0, 2, v2
	v_lshl_add_u32 v56, s37, 6, v3
	v_mov_b32_e32 v2, v1
	v_mov_b32_e32 v3, v1
	s_lshl_b32 s36, s36, 6
	v_and_b32_e32 v41, 60, v0
	v_mov_b32_e32 v0, v1
	v_mov_b64_e32 v[18:19], v[2:3]
	v_or_b32_e32 v43, s36, v41
	s_ashr_i32 s37, s36, 31
	v_cmp_gt_i32_e32 vcc, s64, v56
	v_mov_b64_e32 v[16:17], v[0:1]
	s_and_saveexec_b64 s[38:39], vcc
	s_cbranch_execz .LBB0_1326
	v_mov_b32_e32 v2, v1
	v_mov_b32_e32 v3, v1
	v_mov_b32_e32 v0, v1
	v_mov_b64_e32 v[18:19], v[2:3]
	v_cmp_gt_i32_e32 vcc, s68, v43
	v_mov_b64_e32 v[16:17], v[0:1]
	s_and_saveexec_b64 s[40:41], vcc
	s_cbranch_execz .LBB0_1319
	v_mad_i64_i32 v[2:3], s[78:79], v56, s68, 0
	v_lshl_add_u64 v[2:3], v[2:3], 2, s[4:5]
	v_lshl_add_u64 v[2:3], s[36:37], 2, v[2:3]
	v_lshlrev_b32_e32 v0, 2, v41
	v_lshl_add_u64 v[2:3], v[2:3], 0, v[0:1]
	global_load_dwordx4 v[16:19], v[2:3], off
	s_cmp_lt_i32 s64, 64
	s_cbranch_scc1 .Lc3_skip18
	s_and_b32 s98, s68, 63
	s_cmp_lg_u32 s98, 0
	s_cbranch_scc1 .Lc3_skip18
	s_lshl_b32 s98, s68, 7
	v_add_co_u32_e32 v70, vcc, s98, v2
	s_nop 1
	v_addc_co_u32_e32 v71, vcc, 0, v3, vcc
	s_cmp_lg_u32 s70, 0
	s_cbranch_scc1 .Lc3_pf18
	v_mov_b32_e32 v44, 1.0
	v_mov_b32_e32 v50, 1.0
	global_load_dwordx4 v[32:35], v[70:71], off
	s_cmp_lg_u64 s[30:31], 0
	s_cbranch_scc0 .Lc3_ns18
	v_mov_b32_e32 v67, 0
	v_mov_b32_e32 v66, v56
	v_lshl_add_u64 v[68:69], v[66:67], 2, s[8:9]
	global_load_dword v44, v[68:69], off
	global_load_dword v50, v[68:69], off offset:128
	s_branch .Lc3_fin18

.LBB0_1338:
	s_abs_i32 s36, s42
	s_waitcnt vmcnt(0)
	v_cvt_f32_u32_e32 v0, s36
	s_sub_i32 s39, 0, s36
	s_abs_i32 s38, s45
	s_xor_b32 s37, s45, s42
	v_rcp_iflag_f32_e32 v0, v0
	s_ashr_i32 s37, s37, 31
	v_mov_b32_e32 v2, v202
	v_mul_f32_e32 v0, 0x4f7ffffe, v0
	v_cvt_u32_f32_e32 v0, v0
	v_ashrrev_i32_e32 v3, 4, v2
	v_mov_b32_e32 v42, 1.0
	v_readfirstlane_b32 s40, v0
	s_mul_i32 s39, s39, s40
	s_mul_hi_u32 s39, s40, s39
	s_add_i32 s40, s40, s39
	s_mul_hi_u32 s39, s38, s40
	s_mul_i32 s40, s39, s36
	s_sub_i32 s38, s38, s40
	s_add_i32 s41, s39, 1
	s_sub_i32 s40, s38, s36
	s_cmp_ge_u32 s38, s36
	s_cselect_b32 s39, s41, s39
	s_cselect_b32 s38, s40, s38
	s_add_i32 s40, s39, 1
	s_cmp_ge_u32 s38, s36
	s_cselect_b32 s36, s40, s39
	s_xor_b32 s36, s36, s37
	s_sub_i32 s37, s36, s37
	s_mul_i32 s36, s37, s42
	s_sub_i32 s36, s45, s36
	v_lshlrev_b32_e32 v0, 2, v2
	v_lshl_add_u32 v56, s37, 6, v3
	v_mov_b32_e32 v2, v1
	v_mov_b32_e32 v3, v1
	s_lshl_b32 s36, s36, 6
	v_and_b32_e32 v41, 60, v0
	v_mov_b32_e32 v0, v1
	s_waitcnt lgkmcnt(0)
	v_mov_b64_e32 v[10:11], v[2:3]
	v_or_b32_e32 v43, s36, v41
	s_ashr_i32 s37, s36, 31
	v_cmp_gt_i32_e32 vcc, s64, v56
	v_mov_b64_e32 v[8:9], v[0:1]
	s_and_saveexec_b64 s[38:39], vcc
	s_cbranch_execz .LBB0_1348
	v_mov_b32_e32 v2, v1
	v_mov_b32_e32 v3, v1
	v_mov_b32_e32 v0, v1
	v_mov_b64_e32 v[10:11], v[2:3]
	v_cmp_gt_i32_e32 vcc, s68, v43
	v_mov_b64_e32 v[8:9], v[0:1]
	s_and_saveexec_b64 s[40:41], vcc
	s_cbranch_execz .LBB0_1341
	v_mad_i64_i32 v[2:3], s[78:79], v56, s68, 0
	v_lshl_add_u64 v[2:3], v[2:3], 2, s[4:5]
	v_lshl_add_u64 v[2:3], s[36:37], 2, v[2:3]
	v_lshlrev_b32_e32 v0, 2, v41
	v_lshl_add_u64 v[2:3], v[2:3], 0, v[0:1]
	global_load_dwordx4 v[8:11], v[2:3], off
	s_cmp_lt_i32 s64, 64
	s_cbranch_scc1 .Lc3_skip19
	s_and_b32 s98, s68, 63
	s_cmp_lg_u32 s98, 0
	s_cbranch_scc1 .Lc3_skip19
	s_lshl_b32 s98, s68, 7
	v_add_co_u32_e32 v70, vcc, s98, v2
	s_nop 1
	v_addc_co_u32_e32 v71, vcc, 0, v3, vcc
	s_cmp_lg_u32 s70, 0
	s_cbranch_scc1 .Lc3_pf19
	v_mov_b32_e32 v42, 1.0
	v_mov_b32_e32 v54, 1.0
	global_load_dwordx4 v[24:27], v[70:71], off
	s_cmp_lg_u64 s[30:31], 0
	s_cbranch_scc0 .Lc3_ns19
	v_mov_b32_e32 v67, 0
	v_mov_b32_e32 v66, v56
	v_lshl_add_u64 v[68:69], v[66:67], 2, s[8:9]
	global_load_dword v42, v[68:69], off
	global_load_dword v54, v[68:69], off offset:128
	s_branch .Lc3_fin19

.LBB0_1360:
	s_abs_i32 s35, s76
	s_mul_hi_u32 s36, s35, s83
	s_mul_i32 s37, s36, s77
	s_ashr_i32 s34, s76, 31
	s_sub_i32 s35, s35, s37
	s_xor_b32 s34, s34, s78
	s_add_i32 s37, s36, 1
	s_sub_i32 s38, s35, s77
	s_cmp_eq_u32 s101, 0
	s_cbranch_scc1 .Lc3_w0_8
	s_cmp_eq_u32 s101, 1
	s_cbranch_scc1 .Lc3_w4_8
	s_cmp_eq_u32 s101, 2
	s_cbranch_scc1 .Lc3_w8_8
	s_waitcnt vmcnt(12)
	s_branch .Lc3_wd_8

.Lc3_wd_8:
	v_mov_b32_e32 v0, v202
	s_cmp_ge_u32 s35, s77
	s_cselect_b32 s36, s37, s36
	v_ashrrev_i32_e32 v2, 4, v0
	v_lshlrev_b32_e32 v3, 4, v0
	s_cselect_b32 s35, s38, s35
	s_add_i32 s37, s36, 1
	v_and_b32_e32 v3, 0xf0, v3
	v_mul_lo_u32 v2, v2, s3
	s_cmp_ge_u32 s35, s77
	v_add3_u32 v41, 0, v3, v2
	v_pk_mul_f32 v[2:3], v[46:47], v[20:21] op_sel_hi:[0,1]
	s_cselect_b32 s35, s37, s36
	ds_write2_b32 v41, v2, v3 offset1:1
	v_pk_mul_f32 v[2:3], v[46:47], v[22:23] op_sel_hi:[0,1]
	s_xor_b32 s35, s35, s34
	ds_write2_b32 v41, v2, v3 offset0:2 offset1:3
	v_add_u32_e32 v43, 0x2080, v41
	v_pk_mul_f32 v[2:3], v[52:53], v[36:37] op_sel_hi:[0,1]
	s_sub_i32 s36, s35, s34
	ds_write2_b32 v43, v2, v3 offset1:1
	v_add_u32_e32 v41, 0x2088, v41
	v_pk_mul_f32 v[2:3], v[52:53], v[38:39] op_sel_hi:[0,1]
	ds_write2_b32 v41, v2, v3 offset1:1
	v_ashrrev_i32_e32 v2, 3, v0
	s_mul_i32 s34, s79, s36
	s_waitcnt lgkmcnt(0)
	s_barrier
	v_subrev_u32_e32 v3, s34, v2
	v_add_u32_e32 v41, s82, v3
	v_cmp_gt_i32_e32 vcc, s68, v41
	s_and_saveexec_b64 s[34:35], vcc
	s_cbranch_execz .LBB0_1373
	v_lshlrev_b32_e32 v0, 3, v0
	s_lshl_b32 s36, s36, 6
	v_and_b32_e32 v0, 56, v0
	v_or_b32_e32 v3, s36, v0
	v_cmp_gt_i32_e32 vcc, s65, v3
	s_and_b64 exec, exec, vcc
	s_cbranch_execz .LBB0_1373
	v_lshlrev_b32_e32 v45, 2, v2
	v_mul_u32_u24_e32 v2, 0x104, v0
	v_add3_u32 v43, 0, v45, v2
	ds_read2_b32 v[2:3], v43 offset1:65
	ds_read2_b32 v[56:57], v43 offset0:130 offset1:195
	v_add_u32_e32 v43, 0x400, v43
	ds_read2_b32 v[58:59], v43 offset0:4 offset1:69
	ds_read2_b32 v[60:61], v43 offset0:134 offset1:199
	s_mov_b64 s[42:43], -1
	s_mov_b64 s[38:39], 0
	s_cmp_lt_i32 s69, 2
	s_mov_b64 s[40:41], 0
	s_cbranch_scc1 .LBB0_1368
	s_cmp_eq_u32 s69, 2
	s_mov_b64 s[40:41], -1
	s_cbranch_scc0 .LBB0_1365
	v_and_b32_e32 v43, 0x80, v45
	v_lshrrev_b32_e32 v45, 1, v41
	v_and_b32_e32 v45, 0x60, v45
	v_and_b32_e32 v47, 0xffffff1f, v41
	v_or3_b32 v43, v47, v43, v45
	s_mov_b64 s[40:41], 0

.LBB0_1373:
	s_or_b64 exec, exec, s[34:35]
	s_add_i32 s85, s76, s94
	s_waitcnt lgkmcnt(0)
	s_barrier
	s_add_i32 s100, s101, 1
	s_min_u32 s100, s100, 3
	s_mov_b32 s101, 0
	s_cmp_ge_i32 s85, s72
	s_cselect_b64 s[34:35], -1, 0
	s_and_b64 vcc, exec, s[34:35]
	s_cbranch_vccnz .LBB0_1401
	s_abs_i32 s37, s85
	s_mul_hi_u32 s38, s37, s83
	s_mul_i32 s39, s38, s77
	s_ashr_i32 s36, s85, 31
	s_sub_i32 s37, s37, s39
	s_xor_b32 s36, s36, s78
	s_add_i32 s39, s38, 1
	s_sub_i32 s40, s37, s77
	s_cmp_ge_u32 s37, s77
	s_cselect_b32 s38, s39, s38
	s_cselect_b32 s37, s40, s37
	s_add_i32 s39, s38, 1
	s_cmp_ge_u32 s37, s77
	v_mov_b32_e32 v0, v202
	s_cselect_b32 s37, s39, s38
	s_xor_b32 s37, s37, s36
	s_sub_i32 s37, s37, s36
	v_ashrrev_i32_e32 v2, 4, v0
	v_lshlrev_b32_e32 v0, 2, v0
	s_mul_i32 s36, s84, s37
	v_and_b32_e32 v41, 60, v0
	v_lshl_add_u32 v56, s37, 6, v2
	s_mul_i32 s37, s79, s37
	s_add_i32 s38, s29, s82
	v_subrev_u32_e32 v0, s37, v41
	v_mov_b32_e32 v2, v1
	v_mov_b32_e32 v3, v1
	s_add_i32 s36, s38, s36
	v_add_u32_e32 v43, s38, v0
	v_mov_b32_e32 v0, v1
	v_mov_b64_e32 v[22:23], v[2:3]
	s_ashr_i32 s37, s36, 31
	v_cmp_gt_i32_e32 vcc, s64, v56
	v_mov_b32_e32 v46, 1.0
	v_mov_b64_e32 v[20:21], v[0:1]
	s_and_saveexec_b64 s[38:39], vcc
	s_cbranch_execz .LBB0_1387
	v_mov_b32_e32 v2, v1
	v_mov_b32_e32 v3, v1
	v_mov_b32_e32 v0, v1
	v_mov_b64_e32 v[22:23], v[2:3]
	v_cmp_gt_i32_e32 vcc, s68, v43
	v_mov_b64_e32 v[20:21], v[0:1]
	s_and_saveexec_b64 s[40:41], vcc
	s_cbranch_execz .LBB0_1377
	v_mad_i64_i32 v[2:3], s[42:43], v56, s68, 0
	v_lshl_add_u64 v[2:3], v[2:3], 2, s[4:5]
	v_lshl_add_u64 v[2:3], s[36:37], 2, v[2:3]
	v_lshlrev_b32_e32 v0, 2, v41
	v_lshl_add_u64 v[2:3], v[2:3], 0, v[0:1]
	global_load_dwordx4 v[20:23], v[2:3], off
	s_cmp_lt_i32 s64, 64
	s_cbranch_scc1 .Lc3_skip20
	s_and_b32 s98, s68, 63
	s_cmp_lg_u32 s98, 0
	s_cbranch_scc1 .Lc3_skip20
	s_lshl_b32 s98, s68, 7
	v_add_co_u32_e32 v70, vcc, s98, v2
	s_nop 1
	v_addc_co_u32_e32 v71, vcc, 0, v3, vcc
	s_cmp_lg_u32 s70, 0
	s_cbranch_scc1 .Lc3_pf20
	v_mov_b32_e32 v46, 1.0
	v_mov_b32_e32 v52, 1.0
	global_load_dwordx4 v[36:39], v[70:71], off
	s_cmp_lg_u64 s[30:31], 0
	s_cbranch_scc0 .Lc3_ns20
	v_mov_b32_e32 v67, 0
	v_mov_b32_e32 v66, v56
	v_lshl_add_u64 v[68:69], v[66:67], 2, s[8:9]
	global_load_dword v46, v[68:69], off
	global_load_dword v52, v[68:69], off offset:128
	s_branch .Lc3_fin20

.Lc3_end20:
.LBB0_1401:
	s_add_i32 s36, s28, s76
	s_cmp_ge_i32 s36, s72
	s_cbranch_scc1 .LBB0_1443
	s_ashr_i32 s37, s36, 31
	s_abs_i32 s36, s36
	s_mul_hi_u32 s38, s36, s83
	s_mul_i32 s39, s38, s77
	s_sub_i32 s36, s36, s39
	s_xor_b32 s37, s37, s78
	s_add_i32 s39, s38, 1
	s_sub_i32 s40, s36, s77
	s_cmp_eq_u32 s101, 0
	s_cbranch_scc1 .Lc3_w0_9
	s_cmp_eq_u32 s101, 1
	s_cbranch_scc1 .Lc3_w4_9
	s_cmp_eq_u32 s101, 2
	s_cbranch_scc1 .Lc3_w8_9
	s_waitcnt vmcnt(12)
	s_branch .Lc3_wd_9

.Lc3_wd_9:
	v_mov_b32_e32 v0, v202
	s_cmp_ge_u32 s36, s77
	s_cselect_b32 s38, s39, s38
	v_ashrrev_i32_e32 v2, 4, v0
	v_lshlrev_b32_e32 v3, 4, v0
	s_cselect_b32 s36, s40, s36
	s_add_i32 s39, s38, 1
	v_and_b32_e32 v3, 0xf0, v3
	v_mul_lo_u32 v2, v2, s3
	s_cmp_ge_u32 s36, s77
	v_add3_u32 v41, 0, v3, v2
	v_pk_mul_f32 v[2:3], v[44:45], v[16:17] op_sel_hi:[0,1]
	s_cselect_b32 s36, s39, s38
	ds_write2_b32 v41, v2, v3 offset1:1
	v_pk_mul_f32 v[2:3], v[44:45], v[18:19] op_sel_hi:[0,1]
	s_xor_b32 s36, s36, s37
	ds_write2_b32 v41, v2, v3 offset0:2 offset1:3
	v_add_u32_e32 v43, 0x2080, v41
	v_pk_mul_f32 v[2:3], v[50:51], v[32:33] op_sel_hi:[0,1]
	s_sub_i32 s38, s36, s37
	ds_write2_b32 v43, v2, v3 offset1:1
	v_add_u32_e32 v41, 0x2088, v41
	v_pk_mul_f32 v[2:3], v[50:51], v[34:35] op_sel_hi:[0,1]
	ds_write2_b32 v41, v2, v3 offset1:1
	v_ashrrev_i32_e32 v2, 3, v0
	s_mul_i32 s36, s79, s38
	s_waitcnt lgkmcnt(0)
	s_barrier
	v_subrev_u32_e32 v3, s36, v2
	s_add_i32 s36, s80, s82
	v_add_u32_e32 v41, s36, v3
	v_cmp_gt_i32_e32 vcc, s68, v41
	s_and_saveexec_b64 s[36:37], vcc
	s_cbranch_execz .LBB0_1415
	v_lshlrev_b32_e32 v0, 3, v0
	s_lshl_b32 s38, s38, 6
	v_and_b32_e32 v0, 56, v0
	v_or_b32_e32 v3, s38, v0
	v_cmp_gt_i32_e32 vcc, s65, v3
	s_and_b64 exec, exec, vcc
	s_cbranch_execz .LBB0_1415
	v_lshlrev_b32_e32 v45, 2, v2
	v_mul_u32_u24_e32 v2, 0x104, v0
	v_add3_u32 v43, 0, v45, v2
	ds_read2_b32 v[2:3], v43 offset1:65
	ds_read2_b32 v[56:57], v43 offset0:130 offset1:195
	v_add_u32_e32 v43, 0x400, v43
	ds_read2_b32 v[58:59], v43 offset0:4 offset1:69
	ds_read2_b32 v[60:61], v43 offset0:134 offset1:199
	s_mov_b64 s[44:45], -1
	s_mov_b64 s[40:41], 0
	s_cmp_lt_i32 s69, 2
	s_mov_b64 s[42:43], 0
	s_cbranch_scc1 .LBB0_1410
	s_cmp_eq_u32 s69, 2
	s_mov_b64 s[42:43], -1
	s_cbranch_scc0 .LBB0_1407
	v_and_b32_e32 v43, 0x80, v45
	v_lshrrev_b32_e32 v45, 1, v41
	v_and_b32_e32 v45, 0x60, v45
	v_and_b32_e32 v47, 0xffffff1f, v41
	v_or3_b32 v43, v47, v43, v45
	s_mov_b64 s[42:43], 0

.LBB0_1415:
	s_or_b64 exec, exec, s[36:37]
	s_waitcnt lgkmcnt(0)
	s_barrier
	s_mul_i32 s36, s28, 5
	s_add_i32 s36, s36, s76
	s_add_i32 s100, s101, 1
	s_min_u32 s100, s100, 3
	s_mov_b32 s101, 0
	s_cmp_ge_i32 s36, s72
	s_cbranch_scc1 .LBB0_1443
	s_ashr_i32 s37, s36, 31
	s_abs_i32 s36, s36
	s_mul_hi_u32 s38, s36, s83
	s_mul_i32 s39, s38, s77
	s_sub_i32 s36, s36, s39
	s_xor_b32 s37, s37, s78
	s_add_i32 s39, s38, 1
	s_sub_i32 s40, s36, s77
	s_cmp_ge_u32 s36, s77
	s_cselect_b32 s38, s39, s38
	s_cselect_b32 s36, s40, s36
	s_add_i32 s39, s38, 1
	s_cmp_ge_u32 s36, s77
	v_mov_b32_e32 v0, v202
	s_cselect_b32 s36, s39, s38
	s_xor_b32 s36, s36, s37
	s_sub_i32 s37, s36, s37
	v_ashrrev_i32_e32 v2, 4, v0
	v_lshlrev_b32_e32 v0, 2, v0
	s_mul_i32 s36, s84, s37
	s_mul_i32 s38, s28, 0x140
	v_and_b32_e32 v41, 60, v0
	v_lshl_add_u32 v56, s37, 6, v2
	s_mul_i32 s37, s79, s37
	s_add_i32 s38, s38, s82
	v_subrev_u32_e32 v0, s37, v41
	v_mov_b32_e32 v2, v1
	v_mov_b32_e32 v3, v1
	s_add_i32 s36, s38, s36
	v_add_u32_e32 v43, s38, v0
	v_mov_b32_e32 v0, v1
	v_mov_b64_e32 v[18:19], v[2:3]
	s_ashr_i32 s37, s36, 31
	v_cmp_gt_i32_e32 vcc, s64, v56
	v_mov_b32_e32 v44, 1.0
	v_mov_b64_e32 v[16:17], v[0:1]
	s_and_saveexec_b64 s[38:39], vcc
	s_cbranch_execz .LBB0_1429
	v_mov_b32_e32 v2, v1
	v_mov_b32_e32 v3, v1
	v_mov_b32_e32 v0, v1
	v_mov_b64_e32 v[18:19], v[2:3]
	v_cmp_gt_i32_e32 vcc, s68, v43
	v_mov_b64_e32 v[16:17], v[0:1]
	s_and_saveexec_b64 s[40:41], vcc
	s_cbranch_execz .LBB0_1419
	v_mad_i64_i32 v[2:3], s[42:43], v56, s68, 0
	v_lshl_add_u64 v[2:3], v[2:3], 2, s[4:5]
	v_lshl_add_u64 v[2:3], s[36:37], 2, v[2:3]
	v_lshlrev_b32_e32 v0, 2, v41
	v_lshl_add_u64 v[2:3], v[2:3], 0, v[0:1]
	global_load_dwordx4 v[16:19], v[2:3], off
	s_cmp_lt_i32 s64, 64
	s_cbranch_scc1 .Lc3_skip21
	s_and_b32 s98, s68, 63
	s_cmp_lg_u32 s98, 0
	s_cbranch_scc1 .Lc3_skip21
	s_lshl_b32 s98, s68, 7
	v_add_co_u32_e32 v70, vcc, s98, v2
	s_nop 1
	v_addc_co_u32_e32 v71, vcc, 0, v3, vcc
	s_cmp_lg_u32 s70, 0
	s_cbranch_scc1 .Lc3_pf21
	v_mov_b32_e32 v44, 1.0
	v_mov_b32_e32 v50, 1.0
	global_load_dwordx4 v[32:35], v[70:71], off
	s_cmp_lg_u64 s[30:31], 0
	s_cbranch_scc0 .Lc3_ns21
	v_mov_b32_e32 v67, 0
	v_mov_b32_e32 v66, v56
	v_lshl_add_u64 v[68:69], v[66:67], 2, s[8:9]
	global_load_dword v44, v[68:69], off
	global_load_dword v50, v[68:69], off offset:128
	s_branch .Lc3_fin21

.Lc3_end21:
.LBB0_1443:
	s_add_i32 s36, s95, s76
	s_cmp_ge_i32 s36, s72
	s_cbranch_scc1 .LBB0_1485
	s_ashr_i32 s37, s36, 31
	s_abs_i32 s36, s36
	s_mul_hi_u32 s38, s36, s83
	s_mul_i32 s39, s38, s77
	s_sub_i32 s36, s36, s39
	s_cmp_eq_u32 s101, 0
	s_cbranch_scc1 .Lc3_w0_10
	s_cmp_eq_u32 s101, 1
	s_cbranch_scc1 .Lc3_w4_10
	s_cmp_eq_u32 s101, 2
	s_cbranch_scc1 .Lc3_w8_10
	s_waitcnt vmcnt(12)
	s_branch .Lc3_wd_10

.Lc3_wd_10:
	v_mov_b32_e32 v0, v202
	s_xor_b32 s37, s37, s78
	s_add_i32 s39, s38, 1
	s_sub_i32 s40, s36, s77
	s_cmp_ge_u32 s36, s77
	v_ashrrev_i32_e32 v2, 4, v0
	v_lshlrev_b32_e32 v3, 4, v0
	s_cselect_b32 s38, s39, s38
	v_and_b32_e32 v3, 0xf0, v3
	v_mul_lo_u32 v2, v2, s3
	s_cselect_b32 s36, s40, s36
	s_add_i32 s39, s38, 1
	v_add3_u32 v41, 0, v3, v2
	s_cmp_ge_u32 s36, s77
	v_pk_mul_f32 v[2:3], v[40:41], v[12:13] op_sel_hi:[0,1]
	s_cselect_b32 s36, s39, s38
	ds_write2_b32 v41, v2, v3 offset1:1
	v_pk_mul_f32 v[2:3], v[40:41], v[14:15] op_sel_hi:[0,1]
	s_xor_b32 s36, s36, s37
	ds_write2_b32 v41, v2, v3 offset0:2 offset1:3
	v_add_u32_e32 v43, 0x2080, v41
	v_pk_mul_f32 v[2:3], v[48:49], v[28:29] op_sel_hi:[0,1]
	s_sub_i32 s38, s36, s37
	ds_write2_b32 v43, v2, v3 offset1:1
	v_add_u32_e32 v41, 0x2088, v41
	v_pk_mul_f32 v[2:3], v[48:49], v[30:31] op_sel_hi:[0,1]
	ds_write2_b32 v41, v2, v3 offset1:1
	v_ashrrev_i32_e32 v2, 3, v0
	s_mul_i32 s36, s79, s38
	s_waitcnt lgkmcnt(0)
	s_barrier
	v_subrev_u32_e32 v3, s36, v2
	s_add_i32 s36, s81, s82
	v_add_u32_e32 v41, s36, v3
	v_cmp_gt_i32_e32 vcc, s68, v41
	s_and_saveexec_b64 s[36:37], vcc
	s_cbranch_execz .LBB0_1457
	v_lshlrev_b32_e32 v0, 3, v0
	s_lshl_b32 s38, s38, 6
	v_and_b32_e32 v0, 56, v0
	v_or_b32_e32 v3, s38, v0
	v_cmp_gt_i32_e32 vcc, s65, v3
	s_and_b64 exec, exec, vcc
	s_cbranch_execz .LBB0_1457
	v_lshlrev_b32_e32 v45, 2, v2
	v_mul_u32_u24_e32 v2, 0x104, v0
	v_add3_u32 v43, 0, v45, v2
	ds_read2_b32 v[2:3], v43 offset1:65
	ds_read2_b32 v[56:57], v43 offset0:130 offset1:195
	v_add_u32_e32 v43, 0x400, v43
	ds_read2_b32 v[58:59], v43 offset0:4 offset1:69
	ds_read2_b32 v[60:61], v43 offset0:134 offset1:199
	s_mov_b64 s[44:45], -1
	s_mov_b64 s[40:41], 0
	s_cmp_lt_i32 s69, 2
	s_mov_b64 s[42:43], 0
	s_cbranch_scc1 .LBB0_1452
	s_cmp_eq_u32 s69, 2
	s_mov_b64 s[42:43], -1
	s_cbranch_scc0 .LBB0_1449
	v_and_b32_e32 v43, 0x80, v45
	v_lshrrev_b32_e32 v45, 1, v41
	v_and_b32_e32 v45, 0x60, v45
	v_and_b32_e32 v47, 0xffffff1f, v41
	v_or3_b32 v43, v47, v43, v45
	s_mov_b64 s[42:43], 0

.LBB0_1457:
	s_or_b64 exec, exec, s[36:37]
	s_waitcnt lgkmcnt(0)
	s_barrier
	s_mul_i32 s36, s28, 6
	s_add_i32 s36, s36, s76
	s_add_i32 s100, s101, 1
	s_min_u32 s100, s100, 3
	s_mov_b32 s101, 0
	s_cmp_ge_i32 s36, s72
	s_cbranch_scc1 .LBB0_1485
	s_ashr_i32 s37, s36, 31
	s_abs_i32 s36, s36
	s_mul_hi_u32 s38, s36, s83
	s_mul_i32 s39, s38, s77
	s_sub_i32 s36, s36, s39
	s_xor_b32 s37, s37, s78
	s_add_i32 s39, s38, 1
	s_sub_i32 s40, s36, s77
	s_cmp_ge_u32 s36, s77
	s_cselect_b32 s38, s39, s38
	s_cselect_b32 s36, s40, s36
	s_add_i32 s39, s38, 1
	s_cmp_ge_u32 s36, s77
	v_mov_b32_e32 v0, v202
	s_cselect_b32 s36, s39, s38
	s_xor_b32 s36, s36, s37
	s_sub_i32 s37, s36, s37
	v_ashrrev_i32_e32 v2, 4, v0
	v_lshlrev_b32_e32 v0, 2, v0
	s_mul_i32 s36, s84, s37
	s_mul_i32 s38, s28, 0x180
	v_and_b32_e32 v41, 60, v0
	v_lshl_add_u32 v56, s37, 6, v2
	s_mul_i32 s37, s79, s37
	s_add_i32 s38, s38, s82
	v_subrev_u32_e32 v0, s37, v41
	v_mov_b32_e32 v2, v1
	v_mov_b32_e32 v3, v1
	s_add_i32 s36, s38, s36
	v_add_u32_e32 v43, s38, v0
	v_mov_b32_e32 v0, v1
	v_mov_b64_e32 v[14:15], v[2:3]
	s_ashr_i32 s37, s36, 31
	v_cmp_gt_i32_e32 vcc, s64, v56
	v_mov_b32_e32 v40, 1.0
	v_mov_b64_e32 v[12:13], v[0:1]
	s_and_saveexec_b64 s[38:39], vcc
	s_cbranch_execz .LBB0_1471
	v_mov_b32_e32 v2, v1
	v_mov_b32_e32 v3, v1
	v_mov_b32_e32 v0, v1
	v_mov_b64_e32 v[14:15], v[2:3]
	v_cmp_gt_i32_e32 vcc, s68, v43
	v_mov_b64_e32 v[12:13], v[0:1]
	s_and_saveexec_b64 s[40:41], vcc
	s_cbranch_execz .LBB0_1461
	v_mad_i64_i32 v[2:3], s[42:43], v56, s68, 0
	v_lshl_add_u64 v[2:3], v[2:3], 2, s[4:5]
	v_lshl_add_u64 v[2:3], s[36:37], 2, v[2:3]
	v_lshlrev_b32_e32 v0, 2, v41
	v_lshl_add_u64 v[2:3], v[2:3], 0, v[0:1]
	global_load_dwordx4 v[12:15], v[2:3], off
	s_cmp_lt_i32 s64, 64
	s_cbranch_scc1 .Lc3_skip22
	s_and_b32 s98, s68, 63
	s_cmp_lg_u32 s98, 0
	s_cbranch_scc1 .Lc3_skip22
	s_lshl_b32 s98, s68, 7
	v_add_co_u32_e32 v70, vcc, s98, v2
	s_nop 1
	v_addc_co_u32_e32 v71, vcc, 0, v3, vcc
	s_cmp_lg_u32 s70, 0
	s_cbranch_scc1 .Lc3_pf22
	v_mov_b32_e32 v40, 1.0
	v_mov_b32_e32 v48, 1.0
	global_load_dwordx4 v[28:31], v[70:71], off
	s_cmp_lg_u64 s[30:31], 0
	s_cbranch_scc0 .Lc3_ns22
	v_mov_b32_e32 v67, 0
	v_mov_b32_e32 v66, v56
	v_lshl_add_u64 v[68:69], v[66:67], 2, s[8:9]
	global_load_dword v40, v[68:69], off
	global_load_dword v48, v[68:69], off offset:128
	s_branch .Lc3_fin22

.Lc3_end22:
.LBB0_1485:
	s_add_i32 s36, s33, s76
	s_cmp_ge_i32 s36, s72
	s_cbranch_scc1 .LBB0_1527
	s_ashr_i32 s37, s36, 31
	s_abs_i32 s36, s36
	s_mul_hi_u32 s38, s36, s83
	s_mul_i32 s39, s38, s77
	s_sub_i32 s36, s36, s39
	s_xor_b32 s37, s37, s78
	s_add_i32 s39, s38, 1
	s_sub_i32 s40, s36, s77
	s_cmp_eq_u32 s101, 0
	s_cbranch_scc1 .Lc3_w0_11
	s_cmp_eq_u32 s101, 1
	s_cbranch_scc1 .Lc3_w4_11
	s_cmp_eq_u32 s101, 2
	s_cbranch_scc1 .Lc3_w8_11
	s_waitcnt vmcnt(12)
	s_branch .Lc3_wd_11

.Lc3_wd_11:
	v_mov_b32_e32 v0, v202
	s_cmp_ge_u32 s36, s77
	s_cselect_b32 s38, s39, s38
	v_ashrrev_i32_e32 v2, 4, v0
	v_lshlrev_b32_e32 v3, 4, v0
	s_cselect_b32 s36, s40, s36
	s_add_i32 s39, s38, 1
	v_and_b32_e32 v3, 0xf0, v3
	v_mul_lo_u32 v2, v2, s3
	s_cmp_ge_u32 s36, s77
	v_add3_u32 v41, 0, v3, v2
	s_waitcnt lgkmcnt(4)
	v_pk_mul_f32 v[2:3], v[8:9], v[42:43] op_sel_hi:[1,0]
	s_cselect_b32 s36, s39, s38
	ds_write2_b32 v41, v2, v3 offset1:1
	v_pk_mul_f32 v[2:3], v[10:11], v[42:43] op_sel_hi:[1,0]
	s_xor_b32 s36, s36, s37
	ds_write2_b32 v41, v2, v3 offset0:2 offset1:3
	v_add_u32_e32 v43, 0x2080, v41
	v_pk_mul_f32 v[2:3], v[24:25], v[54:55] op_sel_hi:[1,0]
	s_sub_i32 s38, s36, s37
	ds_write2_b32 v43, v2, v3 offset1:1
	v_add_u32_e32 v41, 0x2088, v41
	v_pk_mul_f32 v[2:3], v[26:27], v[54:55] op_sel_hi:[1,0]
	ds_write2_b32 v41, v2, v3 offset1:1
	v_ashrrev_i32_e32 v2, 3, v0
	s_mul_i32 s36, s79, s38
	v_subrev_u32_e32 v3, s36, v2
	s_mul_i32 s36, s28, 0xc0
	s_waitcnt lgkmcnt(0)
	s_barrier
	s_add_i32 s36, s36, s82
	v_add_u32_e32 v41, s36, v3
	v_cmp_gt_i32_e32 vcc, s68, v41
	s_and_saveexec_b64 s[36:37], vcc
	s_cbranch_execz .LBB0_1499
	v_lshlrev_b32_e32 v0, 3, v0
	s_lshl_b32 s38, s38, 6
	v_and_b32_e32 v0, 56, v0
	v_or_b32_e32 v3, s38, v0
	v_cmp_gt_i32_e32 vcc, s65, v3
	s_and_b64 exec, exec, vcc
	s_cbranch_execz .LBB0_1499
	v_lshlrev_b32_e32 v45, 2, v2
	v_mul_u32_u24_e32 v2, 0x104, v0
	v_add3_u32 v43, 0, v45, v2
	ds_read2_b32 v[2:3], v43 offset1:65
	ds_read2_b32 v[56:57], v43 offset0:130 offset1:195
	v_add_u32_e32 v43, 0x400, v43
	ds_read2_b32 v[58:59], v43 offset0:4 offset1:69
	ds_read2_b32 v[60:61], v43 offset0:134 offset1:199
	s_mov_b64 s[44:45], -1
	s_mov_b64 s[40:41], 0
	s_cmp_lt_i32 s69, 2
	s_mov_b64 s[42:43], 0
	s_cbranch_scc1 .LBB0_1494
	s_cmp_eq_u32 s69, 2
	s_mov_b64 s[42:43], -1
	s_cbranch_scc0 .LBB0_1491
	v_and_b32_e32 v43, 0x80, v45
	v_lshrrev_b32_e32 v45, 1, v41
	v_and_b32_e32 v45, 0x60, v45
	v_and_b32_e32 v47, 0xffffff1f, v41
	v_or3_b32 v43, v47, v43, v45
	s_mov_b64 s[42:43], 0

.LBB0_1499:
	s_or_b64 exec, exec, s[36:37]
	s_waitcnt lgkmcnt(0)
	s_barrier
	s_mul_i32 s36, s28, 7
	s_add_i32 s36, s36, s76
	s_add_i32 s100, s101, 1
	s_min_u32 s100, s100, 3
	s_mov_b32 s101, 0
	s_cmp_ge_i32 s36, s72
	s_cbranch_scc1 .LBB0_1527
	s_ashr_i32 s37, s36, 31
	s_abs_i32 s36, s36
	s_mul_hi_u32 s38, s36, s83
	s_mul_i32 s39, s38, s77
	s_sub_i32 s36, s36, s39
	s_xor_b32 s37, s37, s78
	s_add_i32 s39, s38, 1
	s_sub_i32 s40, s36, s77
	s_cmp_ge_u32 s36, s77
	s_cselect_b32 s38, s39, s38
	s_cselect_b32 s36, s40, s36
	s_add_i32 s39, s38, 1
	s_cmp_ge_u32 s36, s77
	v_mov_b32_e32 v0, v202
	s_cselect_b32 s36, s39, s38
	s_xor_b32 s36, s36, s37
	s_sub_i32 s37, s36, s37
	v_ashrrev_i32_e32 v2, 4, v0
	v_lshlrev_b32_e32 v0, 2, v0
	s_mul_i32 s36, s84, s37
	s_mul_i32 s38, s28, 0x1c0
	v_and_b32_e32 v41, 60, v0
	v_lshl_add_u32 v56, s37, 6, v2
	s_mul_i32 s37, s79, s37
	s_add_i32 s38, s38, s82
	v_subrev_u32_e32 v0, s37, v41
	v_mov_b32_e32 v2, v1
	v_mov_b32_e32 v3, v1
	s_add_i32 s36, s38, s36
	v_add_u32_e32 v43, s38, v0
	v_mov_b32_e32 v0, v1
	v_mov_b64_e32 v[10:11], v[2:3]
	s_ashr_i32 s37, s36, 31
	v_cmp_gt_i32_e32 vcc, s64, v56
	v_mov_b32_e32 v42, 1.0
	v_mov_b64_e32 v[8:9], v[0:1]
	s_and_saveexec_b64 s[38:39], vcc
	s_cbranch_execz .LBB0_1513
	v_mov_b32_e32 v2, v1
	v_mov_b32_e32 v3, v1
	v_mov_b32_e32 v0, v1
	v_mov_b64_e32 v[10:11], v[2:3]
	v_cmp_gt_i32_e32 vcc, s68, v43
	v_mov_b64_e32 v[8:9], v[0:1]
	s_and_saveexec_b64 s[40:41], vcc
	s_cbranch_execz .LBB0_1503
	v_mad_i64_i32 v[2:3], s[42:43], v56, s68, 0
	v_lshl_add_u64 v[2:3], v[2:3], 2, s[4:5]
	v_lshl_add_u64 v[2:3], s[36:37], 2, v[2:3]
	v_lshlrev_b32_e32 v0, 2, v41
	v_lshl_add_u64 v[2:3], v[2:3], 0, v[0:1]
	global_load_dwordx4 v[8:11], v[2:3], off
	s_cmp_lt_i32 s64, 64
	s_cbranch_scc1 .Lc3_skip23
	s_and_b32 s98, s68, 63
	s_cmp_lg_u32 s98, 0
	s_cbranch_scc1 .Lc3_skip23
	s_lshl_b32 s98, s68, 7
	v_add_co_u32_e32 v70, vcc, s98, v2
	s_nop 1
	v_addc_co_u32_e32 v71, vcc, 0, v3, vcc
	s_cmp_lg_u32 s70, 0
	s_cbranch_scc1 .Lc3_pf23
	v_mov_b32_e32 v42, 1.0
	v_mov_b32_e32 v54, 1.0
	global_load_dwordx4 v[24:27], v[70:71], off
	s_cmp_lg_u64 s[30:31], 0
	s_cbranch_scc0 .Lc3_ns23
	v_mov_b32_e32 v67, 0
	v_mov_b32_e32 v66, v56
	v_lshl_add_u64 v[68:69], v[66:67], 2, s[8:9]
	global_load_dword v42, v[68:69], off
	global_load_dword v54, v[68:69], off offset:128
	s_branch .Lc3_fin23
